# write-through (sc1) 16-byte stores extended to P0 (transposes, xn), the P3 tail (V/K transposes, mLSTM pre-pass) and the P5 filler/mLSTM stores
# baseline (speedup 1.0000x reference)
.LBB0_11:
	s_lshl_b32 s24, s19, 1
	s_lshl_b32 s23, s18, 1
	v_or_b32_e32 v8, s24, v38
	s_add_i32 s35, s24, 4
	v_mov_b32_e32 v49, v9
	v_or_b32_e32 v48, s23, v3
	s_add_i32 s34, s23, 4
	s_add_i32 s41, s24, 8
	v_lshlrev_b64 v[64:65], 9, v[8:9]
	v_or_b32_e32 v8, s35, v38
	v_mov_b32_e32 v51, v9
	s_add_i32 s40, s23, 8
	s_add_i32 s53, s24, 12
	v_lshlrev_b64 v[48:49], 9, v[48:49]
	v_or_b32_e32 v50, s34, v3
	v_lshlrev_b64 v[66:67], 9, v[8:9]
	v_or_b32_e32 v8, s41, v38
	v_mov_b32_e32 v53, v9
	s_add_i32 s52, s23, 12
	s_add_i32 s55, s24, 16
	v_or_b32_e32 v52, s40, v3
	v_lshl_add_u64 v[64:65], v[36:37], 0, v[64:65]
	v_lshl_add_u64 v[48:49], v[36:37], 0, v[48:49]
	v_lshlrev_b64 v[50:51], 9, v[50:51]
	v_lshl_add_u64 v[66:67], v[36:37], 0, v[66:67]
	v_lshlrev_b64 v[68:69], 9, v[8:9]
	v_or_b32_e32 v8, s53, v38
	v_mov_b32_e32 v55, v9
	s_add_i32 s54, s23, 16
	s_add_i32 s56, s23, 20
	s_add_i32 s57, s24, 20
	v_or_b32_e32 v54, s52, v3
	v_lshlrev_b64 v[52:53], 9, v[52:53]
	v_lshl_add_u64 v[50:51], v[36:37], 0, v[50:51]
	global_load_dword v64, v[64:65], off
	s_nop 0
	global_load_dword v65, v[48:49], off
	s_nop 0
	global_load_dword v48, v[66:67], off
	global_load_dword v49, v[50:51], off
	v_lshlrev_b64 v[66:67], 9, v[8:9]
	v_or_b32_e32 v8, s55, v38
	v_mov_b32_e32 v57, v9
	v_mov_b32_e32 v59, v9
	s_add_i32 s58, s23, 24
	s_add_i32 s59, s24, 24
	v_or_b32_e32 v56, s54, v3
	v_or_b32_e32 v58, s56, v3
	v_lshlrev_b64 v[54:55], 9, v[54:55]
	v_lshl_add_u64 v[52:53], v[36:37], 0, v[52:53]
	v_lshl_add_u64 v[50:51], v[36:37], 0, v[68:69]
	v_lshl_add_u64 v[66:67], v[36:37], 0, v[66:67]
	v_lshlrev_b64 v[68:69], 9, v[8:9]
	v_or_b32_e32 v8, s57, v38
	v_mov_b32_e32 v61, v9
	s_add_i32 s61, s24, 28
	v_or_b32_e32 v60, s58, v3
	v_lshlrev_b64 v[56:57], 9, v[56:57]
	v_lshlrev_b64 v[58:59], 9, v[58:59]
	v_lshl_add_u64 v[54:55], v[36:37], 0, v[54:55]
	global_load_dword v50, v[50:51], off
	s_nop 0
	global_load_dword v51, v[52:53], off
	s_nop 0
	global_load_dword v52, v[66:67], off
	global_load_dword v53, v[54:55], off
	v_lshlrev_b64 v[66:67], 9, v[8:9]
	v_or_b32_e32 v8, s59, v38
	s_add_i32 s60, s23, 28
	v_lshlrev_b64 v[60:61], 9, v[60:61]
	v_lshl_add_u64 v[56:57], v[36:37], 0, v[56:57]
	v_lshl_add_u64 v[58:59], v[36:37], 0, v[58:59]
	v_lshl_add_u64 v[54:55], v[36:37], 0, v[68:69]
	v_lshl_add_u64 v[66:67], v[36:37], 0, v[66:67]
	v_lshlrev_b64 v[68:69], 9, v[8:9]
	v_or_b32_e32 v8, s61, v38
	v_mov_b32_e32 v63, v9
	v_or_b32_e32 v62, s60, v3
	v_lshl_add_u64 v[60:61], v[36:37], 0, v[60:61]
	global_load_dword v54, v[54:55], off
	s_nop 0
	global_load_dword v55, v[56:57], off
	s_nop 0
	global_load_dword v56, v[66:67], off
	global_load_dword v57, v[58:59], off
	v_lshl_add_u64 v[58:59], v[36:37], 0, v[68:69]
	v_lshlrev_b64 v[66:67], 9, v[8:9]
	v_lshlrev_b64 v[62:63], 9, v[62:63]
	global_load_dword v58, v[58:59], off
	s_nop 0
	global_load_dword v59, v[60:61], off
	v_lshl_add_u64 v[60:61], v[36:37], 0, v[66:67]
	v_lshl_add_u64 v[62:63], v[36:37], 0, v[62:63]
	global_load_dword v60, v[60:61], off
	s_nop 0
	global_load_dword v61, v[62:63], off
	v_or_b32_e32 v62, s24, v2
	v_mad_u64_u32 v[62:63], s[26:27], v62, s3, v[4:5]
	v_or_b32_e32 v8, s23, v1
	v_or_b32_e32 v63, s35, v2
	v_mad_u64_u32 v[66:67], s[26:27], v8, s3, v[4:5]
	v_or_b32_e32 v8, s34, v1
	v_or_b32_e32 v72, s41, v2
	v_mad_u64_u32 v[68:69], s[26:27], v63, s3, v[4:5]
	v_or_b32_e32 v67, s40, v1
	v_or_b32_e32 v76, s53, v2
	v_mad_u64_u32 v[70:71], s[26:27], v8, s3, v[4:5]
	v_mad_u64_u32 v[72:73], s[26:27], v72, s3, v[4:5]
	v_or_b32_e32 v78, s52, v1
	v_or_b32_e32 v80, s55, v2
	v_mad_u64_u32 v[74:75], s[26:27], v67, s3, v[4:5]
	v_mad_u64_u32 v[76:77], s[26:27], v76, s3, v[4:5]
	v_or_b32_e32 v82, s54, v1
	v_or_b32_e32 v84, s57, v2
	v_mad_u64_u32 v[78:79], s[26:27], v78, s3, v[4:5]
	v_mad_u64_u32 v[80:81], s[26:27], v80, s3, v[4:5]
	v_or_b32_e32 v86, s56, v1
	v_or_b32_e32 v88, s59, v2
	v_mad_u64_u32 v[82:83], s[26:27], v82, s3, v[4:5]
	v_mad_u64_u32 v[84:85], s[26:27], v84, s3, v[4:5]
	s_waitcnt vmcnt(14)
	v_pk_mul_f32 v[64:65], v[64:65], s[10:11] op_sel_hi:[1,0]
	ds_write_b32 v62, v64
	ds_write_b32 v66, v65
	s_waitcnt vmcnt(12)
	v_pk_mul_f32 v[48:49], v[48:49], s[10:11] op_sel_hi:[1,0]
	ds_write_b32 v68, v48
	ds_write_b32 v70, v49
	s_add_i32 s19, s19, 16
	s_add_i32 s18, s18, 16
	s_add_i32 s21, s21, -16
	v_or_b32_e32 v90, s58, v1
	v_or_b32_e32 v92, s61, v2
	v_mad_u64_u32 v[86:87], s[26:27], v86, s3, v[4:5]
	v_mad_u64_u32 v[88:89], s[26:27], v88, s3, v[4:5]
	v_or_b32_e32 v94, s60, v1
	s_cmp_lg_u32 s21, 0
	v_mad_u64_u32 v[90:91], s[26:27], v90, s3, v[4:5]
	v_mad_u64_u32 v[92:93], s[26:27], v92, s3, v[4:5]
	v_mad_u64_u32 v[94:95], s[26:27], v94, s3, v[4:5]
	s_waitcnt vmcnt(10)
	v_pk_mul_f32 v[48:49], v[50:51], s[10:11] op_sel_hi:[1,0]
	ds_write_b32 v72, v48
	ds_write_b32 v74, v49
	s_waitcnt vmcnt(8)
	v_pk_mul_f32 v[48:49], v[52:53], s[10:11] op_sel_hi:[1,0]
	ds_write_b32 v76, v48
	ds_write_b32 v78, v49
	s_waitcnt vmcnt(6)
	v_pk_mul_f32 v[48:49], v[54:55], s[10:11] op_sel_hi:[1,0]
	ds_write_b32 v80, v48
	ds_write_b32 v82, v49
	s_waitcnt vmcnt(4)
	v_pk_mul_f32 v[48:49], v[56:57], s[10:11] op_sel_hi:[1,0]
	ds_write_b32 v84, v48
	ds_write_b32 v86, v49
	s_waitcnt vmcnt(2)
	v_pk_mul_f32 v[48:49], v[58:59], s[10:11] op_sel_hi:[1,0]
	ds_write_b32 v88, v48
	ds_write_b32 v90, v49
	s_waitcnt vmcnt(0)
	v_pk_mul_f32 v[48:49], v[60:61], s[10:11] op_sel_hi:[1,0]
	ds_write_b32 v92, v48
	ds_write_b32 v94, v49
	s_cbranch_scc1 .LBB0_11
	s_lshl_b32 s16, s16, 8
	s_waitcnt lgkmcnt(0)
	s_bitset1_b32 s16, 7
	ds_read2_b32 v[36:37], v40 offset0:33 offset1:41
	ds_read2_b32 v[52:53], v40 offset1:8
	ds_read2_b32 v[54:55], v40 offset0:66 offset1:74
	ds_read2_b32 v[56:57], v40 offset0:99 offset1:107
	ds_read2_b32 v[58:59], v40 offset0:132 offset1:140
	ds_read2_b32 v[60:61], v40 offset0:165 offset1:173
	ds_read2_b32 v[62:63], v40 offset0:198 offset1:206
	ds_read2_b32 v[64:65], v40 offset0:231 offset1:239
	v_add_u32_e32 v68, s16, v44
	s_lshl_b32 s24, s17, 1
	v_ashrrev_i32_e32 v69, 31, v68
	v_lshl_add_u64 v[66:67], v[10:11], 0, s[24:25]
	v_lshlrev_b64 v[68:69], 8, v[68:69]
	s_waitcnt lgkmcnt(6)
	v_cvt_pk_bf16_f32 v48, v52, v36
	v_lshl_add_u64 v[68:69], v[66:67], 0, v[68:69]
	v_add_u32_e32 v36, s16, v45
	s_waitcnt lgkmcnt(4)
	v_cvt_pk_bf16_f32 v49, v54, v56
	s_waitcnt lgkmcnt(2)
	v_cvt_pk_bf16_f32 v50, v58, v60
	s_waitcnt lgkmcnt(0)
	v_cvt_pk_bf16_f32 v51, v62, v64
	global_store_dwordx4 v[68:69], v[48:51], off sc1
	s_nop 1
	v_cvt_pk_bf16_f32 v48, v53, v37
	v_ashrrev_i32_e32 v37, 31, v36
	v_lshlrev_b64 v[36:37], 8, v[36:37]
	v_cvt_pk_bf16_f32 v49, v55, v57
	v_cvt_pk_bf16_f32 v50, v59, v61
	v_cvt_pk_bf16_f32 v51, v63, v65
	v_lshl_add_u64 v[36:37], v[66:67], 0, v[36:37]
	ds_read2_b32 v[52:53], v40 offset0:16 offset1:24
	ds_read2_b32 v[54:55], v40 offset0:49 offset1:57
	ds_read2_b32 v[56:57], v40 offset0:82 offset1:90
	ds_read2_b32 v[58:59], v40 offset0:115 offset1:123
	ds_read2_b32 v[60:61], v40 offset0:148 offset1:156
	ds_read2_b32 v[62:63], v40 offset0:181 offset1:189
	ds_read2_b32 v[64:65], v40 offset0:214 offset1:222
	ds_read2_b32 v[68:69], v40 offset0:247 offset1:255
	global_store_dwordx4 v[36:37], v[48:51], off sc1
	v_add_u32_e32 v36, s16, v46
	v_ashrrev_i32_e32 v37, 31, v36
	v_lshlrev_b64 v[36:37], 8, v[36:37]
	v_lshl_add_u64 v[36:37], v[66:67], 0, v[36:37]
	s_waitcnt lgkmcnt(6)
	v_cvt_pk_bf16_f32 v48, v52, v54
	s_waitcnt lgkmcnt(4)
	v_cvt_pk_bf16_f32 v49, v56, v58
	s_waitcnt lgkmcnt(2)
	v_cvt_pk_bf16_f32 v50, v60, v62
	s_waitcnt lgkmcnt(0)
	v_cvt_pk_bf16_f32 v51, v64, v68
	global_store_dwordx4 v[36:37], v[48:51], off sc1
	v_add_u32_e32 v36, s16, v47
	v_ashrrev_i32_e32 v37, 31, v36
	v_lshlrev_b64 v[36:37], 8, v[36:37]
	v_lshl_add_u64 v[36:37], v[66:67], 0, v[36:37]
	v_cvt_pk_bf16_f32 v48, v53, v55
	v_cvt_pk_bf16_f32 v49, v57, v59
	v_cvt_pk_bf16_f32 v50, v61, v63
	v_cvt_pk_bf16_f32 v51, v65, v69
	global_store_dwordx4 v[36:37], v[48:51], off sc1
	s_waitcnt lgkmcnt(0)
	s_mov_b64 s[16:17], 0

.LBB0_15:
	s_lshl_b32 s23, s18, 1
	s_lshl_b32 s24, s19, 1
	v_or_b32_e32 v8, s24, v38
	s_add_i32 s34, s23, 4
	s_add_i32 s35, s24, 4
	v_mov_b32_e32 v51, v9
	s_add_i32 s41, s24, 8
	v_lshlrev_b64 v[64:65], 9, v[8:9]
	v_or_b32_e32 v50, s34, v3
	v_or_b32_e32 v8, s35, v38
	v_mov_b32_e32 v49, v9
	v_or_b32_e32 v48, s23, v3
	s_add_i32 s53, s24, 12
	v_lshlrev_b64 v[50:51], 9, v[50:51]
	v_lshlrev_b64 v[66:67], 9, v[8:9]
	v_or_b32_e32 v8, s41, v38
	s_add_i32 s40, s23, 8
	s_add_i32 s52, s23, 12
	s_add_i32 s55, s24, 16
	v_lshlrev_b64 v[48:49], 9, v[48:49]
	v_lshl_add_u64 v[64:65], v[36:37], 0, v[64:65]
	v_lshl_add_u64 v[50:51], v[36:37], 0, v[50:51]
	v_lshlrev_b64 v[68:69], 9, v[8:9]
	v_or_b32_e32 v8, s53, v38
	v_mov_b32_e32 v53, v9
	v_mov_b32_e32 v55, v9
	s_add_i32 s57, s24, 20
	v_or_b32_e32 v52, s40, v3
	v_or_b32_e32 v54, s52, v3
	v_lshl_add_u64 v[48:49], v[36:37], 0, v[48:49]
	v_lshl_add_u64 v[66:67], v[36:37], 0, v[66:67]
	global_load_dword v80, v[64:65], off
	global_load_dword v81, v[48:49], off
	global_load_dword v82, v[66:67], off
	global_load_dword v83, v[50:51], off
	v_lshlrev_b64 v[50:51], 9, v[8:9]
	v_or_b32_e32 v8, s55, v38
	s_add_i32 s54, s23, 16
	s_add_i32 s56, s23, 20
	s_add_i32 s59, s24, 24
	v_lshlrev_b64 v[52:53], 9, v[52:53]
	v_lshlrev_b64 v[54:55], 9, v[54:55]
	v_lshl_add_u64 v[48:49], v[36:37], 0, v[68:69]
	v_lshl_add_u64 v[50:51], v[36:37], 0, v[50:51]
	v_lshlrev_b64 v[64:65], 9, v[8:9]
	v_or_b32_e32 v8, s57, v38
	v_mov_b32_e32 v57, v9
	v_mov_b32_e32 v59, v9
	s_add_i32 s58, s23, 24
	s_add_i32 s60, s23, 28
	s_add_i32 s61, s24, 28
	v_or_b32_e32 v56, s54, v3
	v_or_b32_e32 v58, s56, v3
	v_lshl_add_u64 v[52:53], v[36:37], 0, v[52:53]
	v_lshl_add_u64 v[54:55], v[36:37], 0, v[54:55]
	global_load_dword v84, v[48:49], off
	global_load_dword v85, v[52:53], off
	global_load_dword v86, v[50:51], off
	global_load_dword v87, v[54:55], off
	v_lshlrev_b64 v[50:51], 9, v[8:9]
	v_or_b32_e32 v8, s59, v38
	v_mov_b32_e32 v61, v9
	v_mov_b32_e32 v63, v9
	v_or_b32_e32 v60, s58, v3
	v_or_b32_e32 v62, s60, v3
	v_lshlrev_b64 v[56:57], 9, v[56:57]
	v_lshlrev_b64 v[58:59], 9, v[58:59]
	v_lshl_add_u64 v[48:49], v[36:37], 0, v[64:65]
	v_lshl_add_u64 v[50:51], v[36:37], 0, v[50:51]
	v_lshlrev_b64 v[52:53], 9, v[8:9]
	v_or_b32_e32 v8, s61, v38
	v_lshlrev_b64 v[60:61], 9, v[60:61]
	v_lshlrev_b64 v[62:63], 9, v[62:63]
	v_lshl_add_u64 v[56:57], v[36:37], 0, v[56:57]
	v_lshl_add_u64 v[58:59], v[36:37], 0, v[58:59]
	global_load_dword v88, v[48:49], off
	global_load_dword v89, v[56:57], off
	global_load_dword v90, v[50:51], off
	global_load_dword v91, v[58:59], off
	v_lshl_add_u64 v[48:49], v[36:37], 0, v[52:53]
	v_lshlrev_b64 v[50:51], 9, v[8:9]
	v_lshl_add_u64 v[60:61], v[36:37], 0, v[60:61]
	v_lshl_add_u64 v[62:63], v[36:37], 0, v[62:63]
	v_lshl_add_u64 v[50:51], v[36:37], 0, v[50:51]
	global_load_dword v8, v[48:49], off
	global_load_dword v92, v[60:61], off
	global_load_dword v93, v[50:51], off
	global_load_dword v94, v[62:63], off
	v_or_b32_e32 v50, s23, v1
	v_or_b32_e32 v48, s24, v2
	s_add_i32 s19, s19, 16
	s_add_i32 s18, s18, 16
	s_add_i32 s21, s21, -16
	v_mad_u64_u32 v[48:49], s[26:27], v48, s3, v[4:5]
	v_mad_u64_u32 v[50:51], s[26:27], v50, s3, v[4:5]
	v_or_b32_e32 v49, s34, v1
	v_or_b32_e32 v51, s35, v2
	v_or_b32_e32 v58, s40, v1
	v_or_b32_e32 v56, s41, v2
	v_or_b32_e32 v62, s52, v1
	v_or_b32_e32 v60, s53, v2
	v_or_b32_e32 v66, s54, v1
	v_or_b32_e32 v64, s55, v2
	v_or_b32_e32 v70, s56, v1
	v_or_b32_e32 v68, s57, v2
	v_or_b32_e32 v74, s58, v1
	v_or_b32_e32 v72, s59, v2
	v_or_b32_e32 v78, s60, v1
	v_or_b32_e32 v76, s61, v2
	s_cmp_lg_u32 s21, 0
	v_mad_u64_u32 v[52:53], s[26:27], v51, s3, v[4:5]
	v_mad_u64_u32 v[54:55], s[26:27], v49, s3, v[4:5]
	v_mad_u64_u32 v[56:57], s[26:27], v56, s3, v[4:5]
	v_mad_u64_u32 v[58:59], s[26:27], v58, s3, v[4:5]
	v_mad_u64_u32 v[60:61], s[26:27], v60, s3, v[4:5]
	v_mad_u64_u32 v[62:63], s[26:27], v62, s3, v[4:5]
	v_mad_u64_u32 v[64:65], s[26:27], v64, s3, v[4:5]
	v_mad_u64_u32 v[66:67], s[26:27], v66, s3, v[4:5]
	v_mad_u64_u32 v[68:69], s[26:27], v68, s3, v[4:5]
	v_mad_u64_u32 v[70:71], s[26:27], v70, s3, v[4:5]
	v_mad_u64_u32 v[72:73], s[26:27], v72, s3, v[4:5]
	v_mad_u64_u32 v[74:75], s[26:27], v74, s3, v[4:5]
	v_mad_u64_u32 v[76:77], s[26:27], v76, s3, v[4:5]
	v_mad_u64_u32 v[78:79], s[26:27], v78, s3, v[4:5]
	s_waitcnt vmcnt(15)
	ds_write_b32 v48, v80
	s_waitcnt vmcnt(14)
	ds_write_b32 v50, v81
	s_waitcnt vmcnt(13)
	ds_write_b32 v52, v82
	s_waitcnt vmcnt(12)
	ds_write_b32 v54, v83
	s_waitcnt vmcnt(11)
	ds_write_b32 v56, v84
	s_waitcnt vmcnt(10)
	ds_write_b32 v58, v85
	s_waitcnt vmcnt(9)
	ds_write_b32 v60, v86
	s_waitcnt vmcnt(8)
	ds_write_b32 v62, v87
	s_waitcnt vmcnt(7)
	ds_write_b32 v64, v88
	s_waitcnt vmcnt(6)
	ds_write_b32 v66, v89
	s_waitcnt vmcnt(5)
	ds_write_b32 v68, v90
	s_waitcnt vmcnt(4)
	ds_write_b32 v70, v91
	s_waitcnt vmcnt(3)
	ds_write_b32 v72, v8
	s_waitcnt vmcnt(2)
	ds_write_b32 v74, v92
	s_waitcnt vmcnt(1)
	ds_write_b32 v76, v93
	s_waitcnt vmcnt(0)
	ds_write_b32 v78, v94
	s_cbranch_scc1 .LBB0_15
	s_lshl_b32 s16, s16, 8
	s_waitcnt lgkmcnt(0)
	ds_read2_b32 v[36:37], v40 offset0:33 offset1:41
	ds_read2_b32 v[52:53], v40 offset1:8
	ds_read2_b32 v[54:55], v40 offset0:66 offset1:74
	ds_read2_b32 v[56:57], v40 offset0:99 offset1:107
	ds_read2_b32 v[58:59], v40 offset0:132 offset1:140
	ds_read2_b32 v[60:61], v40 offset0:165 offset1:173
	ds_read2_b32 v[62:63], v40 offset0:198 offset1:206
	ds_read2_b32 v[64:65], v40 offset0:231 offset1:239
	v_or_b32_e32 v3, s16, v5
	v_add_u32_e32 v68, s6, v3
	s_lshl_b32 s24, s17, 1
	v_ashrrev_i32_e32 v69, 31, v68
	v_lshl_add_u64 v[66:67], v[10:11], 0, s[24:25]
	v_lshlrev_b64 v[68:69], 8, v[68:69]
	v_or_b32_e32 v3, s16, v41
	s_waitcnt lgkmcnt(6)
	v_cvt_pk_bf16_f32 v48, v52, v36
	v_lshl_add_u64 v[68:69], v[66:67], 0, v[68:69]
	v_add_u32_e32 v36, s6, v3
	s_waitcnt lgkmcnt(4)
	v_cvt_pk_bf16_f32 v49, v54, v56
	s_waitcnt lgkmcnt(2)
	v_cvt_pk_bf16_f32 v50, v58, v60
	s_waitcnt lgkmcnt(0)
	v_cvt_pk_bf16_f32 v51, v62, v64
	global_store_dwordx4 v[68:69], v[48:51], off sc1
	v_or_b32_e32 v3, s16, v42
	s_nop 0
	v_cvt_pk_bf16_f32 v48, v53, v37
	v_ashrrev_i32_e32 v37, 31, v36
	v_lshlrev_b64 v[36:37], 8, v[36:37]
	v_cvt_pk_bf16_f32 v49, v55, v57
	v_cvt_pk_bf16_f32 v50, v59, v61
	v_cvt_pk_bf16_f32 v51, v63, v65
	v_lshl_add_u64 v[36:37], v[66:67], 0, v[36:37]
	ds_read2_b32 v[52:53], v40 offset0:16 offset1:24
	ds_read2_b32 v[54:55], v40 offset0:49 offset1:57
	ds_read2_b32 v[56:57], v40 offset0:82 offset1:90
	ds_read2_b32 v[58:59], v40 offset0:115 offset1:123
	ds_read2_b32 v[60:61], v40 offset0:148 offset1:156
	ds_read2_b32 v[62:63], v40 offset0:181 offset1:189
	ds_read2_b32 v[64:65], v40 offset0:214 offset1:222
	ds_read2_b32 v[68:69], v40 offset0:247 offset1:255
	global_store_dwordx4 v[36:37], v[48:51], off sc1
	v_add_u32_e32 v36, s6, v3
	v_ashrrev_i32_e32 v37, 31, v36
	v_lshlrev_b64 v[36:37], 8, v[36:37]
	v_lshl_add_u64 v[36:37], v[66:67], 0, v[36:37]
	v_or_b32_e32 v3, s16, v43
	s_waitcnt lgkmcnt(6)
	v_cvt_pk_bf16_f32 v48, v52, v54
	s_waitcnt lgkmcnt(4)
	v_cvt_pk_bf16_f32 v49, v56, v58
	s_waitcnt lgkmcnt(2)
	v_cvt_pk_bf16_f32 v50, v60, v62
	s_waitcnt lgkmcnt(0)
	v_cvt_pk_bf16_f32 v51, v64, v68
	global_store_dwordx4 v[36:37], v[48:51], off sc1
	v_add_u32_e32 v36, s6, v3
	v_ashrrev_i32_e32 v37, 31, v36
	v_lshlrev_b64 v[36:37], 8, v[36:37]
	v_lshl_add_u64 v[36:37], v[66:67], 0, v[36:37]
	v_cvt_pk_bf16_f32 v48, v53, v55
	v_cvt_pk_bf16_f32 v49, v57, v59
	v_cvt_pk_bf16_f32 v50, v61, v63
	v_cvt_pk_bf16_f32 v51, v65, v69
	global_store_dwordx4 v[36:37], v[48:51], off sc1
	s_waitcnt lgkmcnt(0)

.LBB0_20:
	s_lshl_b32 s23, s19, 1
	s_lshl_b32 s24, s21, 1
	v_or_b32_e32 v8, s24, v38
	s_add_i32 s34, s23, 4
	s_add_i32 s35, s24, 4
	v_mov_b32_e32 v51, v9
	s_add_i32 s41, s24, 8
	v_lshlrev_b64 v[64:65], 8, v[8:9]
	v_or_b32_e32 v50, s34, v3
	v_or_b32_e32 v8, s35, v38
	v_mov_b32_e32 v49, v9
	v_or_b32_e32 v48, s23, v3
	s_add_i32 s53, s24, 12
	v_lshlrev_b64 v[50:51], 8, v[50:51]
	v_lshlrev_b64 v[66:67], 8, v[8:9]
	v_or_b32_e32 v8, s41, v38
	s_add_i32 s40, s23, 8
	s_add_i32 s52, s23, 12
	s_add_i32 s55, s24, 16
	v_lshlrev_b64 v[48:49], 8, v[48:49]
	v_lshl_add_u64 v[64:65], v[36:37], 0, v[64:65]
	v_lshl_add_u64 v[50:51], v[36:37], 0, v[50:51]
	v_lshlrev_b64 v[68:69], 8, v[8:9]
	v_or_b32_e32 v8, s53, v38
	v_mov_b32_e32 v53, v9
	v_mov_b32_e32 v55, v9
	s_add_i32 s57, s24, 20
	v_or_b32_e32 v52, s40, v3
	v_or_b32_e32 v54, s52, v3
	v_lshl_add_u64 v[48:49], v[36:37], 0, v[48:49]
	v_lshl_add_u64 v[66:67], v[36:37], 0, v[66:67]
	global_load_dword v80, v[64:65], off
	global_load_dword v81, v[48:49], off
	global_load_dword v82, v[66:67], off
	global_load_dword v83, v[50:51], off
	v_lshlrev_b64 v[50:51], 8, v[8:9]
	v_or_b32_e32 v8, s55, v38
	s_add_i32 s54, s23, 16
	s_add_i32 s56, s23, 20
	s_add_i32 s59, s24, 24
	v_lshlrev_b64 v[52:53], 8, v[52:53]
	v_lshlrev_b64 v[54:55], 8, v[54:55]
	v_lshl_add_u64 v[48:49], v[36:37], 0, v[68:69]
	v_lshl_add_u64 v[50:51], v[36:37], 0, v[50:51]
	v_lshlrev_b64 v[64:65], 8, v[8:9]
	v_or_b32_e32 v8, s57, v38
	v_mov_b32_e32 v57, v9
	v_mov_b32_e32 v59, v9
	s_add_i32 s58, s23, 24
	s_add_i32 s60, s23, 28
	s_add_i32 s61, s24, 28
	v_or_b32_e32 v56, s54, v3
	v_or_b32_e32 v58, s56, v3
	v_lshl_add_u64 v[52:53], v[36:37], 0, v[52:53]
	v_lshl_add_u64 v[54:55], v[36:37], 0, v[54:55]
	global_load_dword v84, v[48:49], off
	global_load_dword v85, v[52:53], off
	global_load_dword v86, v[50:51], off
	global_load_dword v87, v[54:55], off
	v_lshlrev_b64 v[50:51], 8, v[8:9]
	v_or_b32_e32 v8, s59, v38
	v_mov_b32_e32 v61, v9
	v_mov_b32_e32 v63, v9
	v_or_b32_e32 v60, s58, v3
	v_or_b32_e32 v62, s60, v3
	v_lshlrev_b64 v[56:57], 8, v[56:57]
	v_lshlrev_b64 v[58:59], 8, v[58:59]
	v_lshl_add_u64 v[48:49], v[36:37], 0, v[64:65]
	v_lshl_add_u64 v[50:51], v[36:37], 0, v[50:51]
	v_lshlrev_b64 v[52:53], 8, v[8:9]
	v_or_b32_e32 v8, s61, v38
	v_lshlrev_b64 v[60:61], 8, v[60:61]
	v_lshlrev_b64 v[62:63], 8, v[62:63]
	v_lshl_add_u64 v[56:57], v[36:37], 0, v[56:57]
	v_lshl_add_u64 v[58:59], v[36:37], 0, v[58:59]
	global_load_dword v88, v[48:49], off
	global_load_dword v89, v[56:57], off
	global_load_dword v90, v[50:51], off
	global_load_dword v91, v[58:59], off
	v_lshl_add_u64 v[48:49], v[36:37], 0, v[52:53]
	v_lshlrev_b64 v[50:51], 8, v[8:9]
	v_lshl_add_u64 v[60:61], v[36:37], 0, v[60:61]
	v_lshl_add_u64 v[62:63], v[36:37], 0, v[62:63]
	v_lshl_add_u64 v[50:51], v[36:37], 0, v[50:51]
	global_load_dword v8, v[48:49], off
	global_load_dword v92, v[60:61], off
	global_load_dword v93, v[50:51], off
	global_load_dword v94, v[62:63], off
	v_or_b32_e32 v50, s23, v1
	v_or_b32_e32 v48, s24, v2
	s_add_i32 s21, s21, 16
	s_add_i32 s19, s19, 16
	s_add_i32 s18, s18, -16
	v_mad_u64_u32 v[48:49], s[26:27], v48, s3, v[4:5]
	v_mad_u64_u32 v[50:51], s[26:27], v50, s3, v[4:5]
	v_or_b32_e32 v49, s34, v1
	v_or_b32_e32 v51, s35, v2
	v_or_b32_e32 v58, s40, v1
	v_or_b32_e32 v56, s41, v2
	v_or_b32_e32 v62, s52, v1
	v_or_b32_e32 v60, s53, v2
	v_or_b32_e32 v66, s54, v1
	v_or_b32_e32 v64, s55, v2
	v_or_b32_e32 v70, s56, v1
	v_or_b32_e32 v68, s57, v2
	v_or_b32_e32 v74, s58, v1
	v_or_b32_e32 v72, s59, v2
	v_or_b32_e32 v78, s60, v1
	v_or_b32_e32 v76, s61, v2
	s_cmp_lg_u32 s18, 0
	v_mad_u64_u32 v[52:53], s[26:27], v51, s3, v[4:5]
	v_mad_u64_u32 v[54:55], s[26:27], v49, s3, v[4:5]
	v_mad_u64_u32 v[56:57], s[26:27], v56, s3, v[4:5]
	v_mad_u64_u32 v[58:59], s[26:27], v58, s3, v[4:5]
	v_mad_u64_u32 v[60:61], s[26:27], v60, s3, v[4:5]
	v_mad_u64_u32 v[62:63], s[26:27], v62, s3, v[4:5]
	v_mad_u64_u32 v[64:65], s[26:27], v64, s3, v[4:5]
	v_mad_u64_u32 v[66:67], s[26:27], v66, s3, v[4:5]
	v_mad_u64_u32 v[68:69], s[26:27], v68, s3, v[4:5]
	v_mad_u64_u32 v[70:71], s[26:27], v70, s3, v[4:5]
	v_mad_u64_u32 v[72:73], s[26:27], v72, s3, v[4:5]
	v_mad_u64_u32 v[74:75], s[26:27], v74, s3, v[4:5]
	v_mad_u64_u32 v[76:77], s[26:27], v76, s3, v[4:5]
	v_mad_u64_u32 v[78:79], s[26:27], v78, s3, v[4:5]
	s_waitcnt vmcnt(15)
	ds_write_b32 v48, v80
	s_waitcnt vmcnt(14)
	ds_write_b32 v50, v81
	s_waitcnt vmcnt(13)
	ds_write_b32 v52, v82
	s_waitcnt vmcnt(12)
	ds_write_b32 v54, v83
	s_waitcnt vmcnt(11)
	ds_write_b32 v56, v84
	s_waitcnt vmcnt(10)
	ds_write_b32 v58, v85
	s_waitcnt vmcnt(9)
	ds_write_b32 v60, v86
	s_waitcnt vmcnt(8)
	ds_write_b32 v62, v87
	s_waitcnt vmcnt(7)
	ds_write_b32 v64, v88
	s_waitcnt vmcnt(6)
	ds_write_b32 v66, v89
	s_waitcnt vmcnt(5)
	ds_write_b32 v68, v90
	s_waitcnt vmcnt(4)
	ds_write_b32 v70, v91
	s_waitcnt vmcnt(3)
	ds_write_b32 v72, v8
	s_waitcnt vmcnt(2)
	ds_write_b32 v74, v92
	s_waitcnt vmcnt(1)
	ds_write_b32 v76, v93
	s_waitcnt vmcnt(0)
	ds_write_b32 v78, v94
	s_cbranch_scc1 .LBB0_20
	s_waitcnt lgkmcnt(0)
	ds_read2_b32 v[52:53], v40 offset0:33 offset1:41
	ds_read2_b32 v[54:55], v40 offset1:8
	ds_read2_b32 v[56:57], v40 offset0:66 offset1:74
	ds_read2_b32 v[58:59], v40 offset0:99 offset1:107
	ds_read2_b32 v[60:61], v40 offset0:132 offset1:140
	ds_read2_b32 v[62:63], v40 offset0:165 offset1:173
	ds_read2_b32 v[64:65], v40 offset0:198 offset1:206
	ds_read2_b32 v[66:67], v40 offset0:231 offset1:239
	s_lshl_b32 s24, s17, 1
	v_or_b32_e32 v3, s16, v5
	v_lshl_add_u64 v[36:37], v[14:15], 0, s[24:25]
	v_lshlrev_b32_e32 v8, 9, v3
	v_or_b32_e32 v3, s16, v41
	s_waitcnt lgkmcnt(6)
	v_cvt_pk_bf16_f32 v48, v54, v52
	v_lshl_add_u64 v[68:69], v[36:37], 0, v[8:9]
	v_lshlrev_b32_e32 v8, 9, v3
	s_waitcnt lgkmcnt(4)
	v_cvt_pk_bf16_f32 v49, v56, v58
	s_waitcnt lgkmcnt(2)
	v_cvt_pk_bf16_f32 v50, v60, v62
	s_waitcnt lgkmcnt(0)
	v_cvt_pk_bf16_f32 v51, v64, v66
	global_store_dwordx4 v[68:69], v[48:51], off sc1
	v_or_b32_e32 v3, s16, v42
	s_nop 0
	v_cvt_pk_bf16_f32 v48, v55, v53
	v_lshl_add_u64 v[52:53], v[36:37], 0, v[8:9]
	v_cvt_pk_bf16_f32 v49, v57, v59
	v_cvt_pk_bf16_f32 v50, v61, v63
	v_cvt_pk_bf16_f32 v51, v65, v67
	global_store_dwordx4 v[52:53], v[48:51], off sc1
	ds_read2_b32 v[52:53], v40 offset0:16 offset1:24
	ds_read2_b32 v[54:55], v40 offset0:49 offset1:57
	ds_read2_b32 v[56:57], v40 offset0:82 offset1:90
	ds_read2_b32 v[58:59], v40 offset0:115 offset1:123
	ds_read2_b32 v[60:61], v40 offset0:148 offset1:156
	ds_read2_b32 v[62:63], v40 offset0:181 offset1:189
	ds_read2_b32 v[64:65], v40 offset0:214 offset1:222
	ds_read2_b32 v[66:67], v40 offset0:247 offset1:255
	v_lshlrev_b32_e32 v8, 9, v3
	v_or_b32_e32 v3, s16, v43
	v_lshl_add_u64 v[68:69], v[36:37], 0, v[8:9]
	v_lshlrev_b32_e32 v8, 9, v3
	s_waitcnt lgkmcnt(6)
	v_cvt_pk_bf16_f32 v48, v52, v54
	s_waitcnt lgkmcnt(4)
	v_cvt_pk_bf16_f32 v49, v56, v58
	s_waitcnt lgkmcnt(2)
	v_cvt_pk_bf16_f32 v50, v60, v62
	s_waitcnt lgkmcnt(0)
	v_cvt_pk_bf16_f32 v51, v64, v66
	v_lshl_add_u64 v[36:37], v[36:37], 0, v[8:9]
	global_store_dwordx4 v[68:69], v[48:51], off sc1
	s_nop 1
	v_cvt_pk_bf16_f32 v48, v53, v55
	v_cvt_pk_bf16_f32 v49, v57, v59
	v_cvt_pk_bf16_f32 v50, v61, v63
	v_cvt_pk_bf16_f32 v51, v65, v67
	global_store_dwordx4 v[36:37], v[48:51], off sc1
	s_waitcnt lgkmcnt(0)

.LBB0_25:
	s_lshl_b32 s23, s19, 1
	s_lshl_b32 s24, s21, 1
	v_or_b32_e32 v8, s24, v38
	s_add_i32 s34, s23, 4
	s_add_i32 s35, s24, 4
	v_mov_b32_e32 v51, v9
	s_add_i32 s41, s24, 8
	v_lshlrev_b64 v[64:65], 8, v[8:9]
	v_or_b32_e32 v50, s34, v3
	v_or_b32_e32 v8, s35, v38
	v_mov_b32_e32 v49, v9
	v_or_b32_e32 v48, s23, v3
	s_add_i32 s53, s24, 12
	v_lshlrev_b64 v[50:51], 8, v[50:51]
	v_lshlrev_b64 v[66:67], 8, v[8:9]
	v_or_b32_e32 v8, s41, v38
	s_add_i32 s40, s23, 8
	s_add_i32 s52, s23, 12
	s_add_i32 s55, s24, 16
	v_lshlrev_b64 v[48:49], 8, v[48:49]
	v_lshl_add_u64 v[64:65], v[36:37], 0, v[64:65]
	v_lshl_add_u64 v[50:51], v[36:37], 0, v[50:51]
	v_lshlrev_b64 v[68:69], 8, v[8:9]
	v_or_b32_e32 v8, s53, v38
	v_mov_b32_e32 v53, v9
	v_mov_b32_e32 v55, v9
	s_add_i32 s57, s24, 20
	v_or_b32_e32 v52, s40, v3
	v_or_b32_e32 v54, s52, v3
	v_lshl_add_u64 v[48:49], v[36:37], 0, v[48:49]
	v_lshl_add_u64 v[66:67], v[36:37], 0, v[66:67]
	global_load_dword v80, v[64:65], off
	global_load_dword v81, v[48:49], off
	global_load_dword v82, v[66:67], off
	global_load_dword v83, v[50:51], off
	v_lshlrev_b64 v[50:51], 8, v[8:9]
	v_or_b32_e32 v8, s55, v38
	s_add_i32 s54, s23, 16
	s_add_i32 s56, s23, 20
	s_add_i32 s59, s24, 24
	v_lshlrev_b64 v[52:53], 8, v[52:53]
	v_lshlrev_b64 v[54:55], 8, v[54:55]
	v_lshl_add_u64 v[48:49], v[36:37], 0, v[68:69]
	v_lshl_add_u64 v[50:51], v[36:37], 0, v[50:51]
	v_lshlrev_b64 v[64:65], 8, v[8:9]
	v_or_b32_e32 v8, s57, v38
	v_mov_b32_e32 v57, v9
	v_mov_b32_e32 v59, v9
	s_add_i32 s58, s23, 24
	s_add_i32 s60, s23, 28
	s_add_i32 s61, s24, 28
	v_or_b32_e32 v56, s54, v3
	v_or_b32_e32 v58, s56, v3
	v_lshl_add_u64 v[52:53], v[36:37], 0, v[52:53]
	v_lshl_add_u64 v[54:55], v[36:37], 0, v[54:55]
	global_load_dword v84, v[48:49], off
	global_load_dword v85, v[52:53], off
	global_load_dword v86, v[50:51], off
	global_load_dword v87, v[54:55], off
	v_lshlrev_b64 v[50:51], 8, v[8:9]
	v_or_b32_e32 v8, s59, v38
	v_mov_b32_e32 v61, v9
	v_mov_b32_e32 v63, v9
	v_or_b32_e32 v60, s58, v3
	v_or_b32_e32 v62, s60, v3
	v_lshlrev_b64 v[56:57], 8, v[56:57]
	v_lshlrev_b64 v[58:59], 8, v[58:59]
	v_lshl_add_u64 v[48:49], v[36:37], 0, v[64:65]
	v_lshl_add_u64 v[50:51], v[36:37], 0, v[50:51]
	v_lshlrev_b64 v[52:53], 8, v[8:9]
	v_or_b32_e32 v8, s61, v38
	v_lshlrev_b64 v[60:61], 8, v[60:61]
	v_lshlrev_b64 v[62:63], 8, v[62:63]
	v_lshl_add_u64 v[56:57], v[36:37], 0, v[56:57]
	v_lshl_add_u64 v[58:59], v[36:37], 0, v[58:59]
	global_load_dword v88, v[48:49], off
	global_load_dword v89, v[56:57], off
	global_load_dword v90, v[50:51], off
	global_load_dword v91, v[58:59], off
	v_lshl_add_u64 v[48:49], v[36:37], 0, v[52:53]
	v_lshlrev_b64 v[50:51], 8, v[8:9]
	v_lshl_add_u64 v[60:61], v[36:37], 0, v[60:61]
	v_lshl_add_u64 v[62:63], v[36:37], 0, v[62:63]
	v_lshl_add_u64 v[50:51], v[36:37], 0, v[50:51]
	global_load_dword v8, v[48:49], off
	global_load_dword v92, v[60:61], off
	global_load_dword v93, v[50:51], off
	global_load_dword v94, v[62:63], off
	v_or_b32_e32 v50, s23, v1
	v_or_b32_e32 v48, s24, v2
	s_add_i32 s21, s21, 16
	s_add_i32 s19, s19, 16
	s_add_i32 s18, s18, -16
	v_mad_u64_u32 v[48:49], s[26:27], v48, s3, v[4:5]
	v_mad_u64_u32 v[50:51], s[26:27], v50, s3, v[4:5]
	v_or_b32_e32 v49, s34, v1
	v_or_b32_e32 v51, s35, v2
	v_or_b32_e32 v58, s40, v1
	v_or_b32_e32 v56, s41, v2
	v_or_b32_e32 v62, s52, v1
	v_or_b32_e32 v60, s53, v2
	v_or_b32_e32 v66, s54, v1
	v_or_b32_e32 v64, s55, v2
	v_or_b32_e32 v70, s56, v1
	v_or_b32_e32 v68, s57, v2
	v_or_b32_e32 v74, s58, v1
	v_or_b32_e32 v72, s59, v2
	v_or_b32_e32 v78, s60, v1
	v_or_b32_e32 v76, s61, v2
	s_cmp_lg_u32 s18, 0
	v_mad_u64_u32 v[52:53], s[26:27], v51, s3, v[4:5]
	v_mad_u64_u32 v[54:55], s[26:27], v49, s3, v[4:5]
	v_mad_u64_u32 v[56:57], s[26:27], v56, s3, v[4:5]
	v_mad_u64_u32 v[58:59], s[26:27], v58, s3, v[4:5]
	v_mad_u64_u32 v[60:61], s[26:27], v60, s3, v[4:5]
	v_mad_u64_u32 v[62:63], s[26:27], v62, s3, v[4:5]
	v_mad_u64_u32 v[64:65], s[26:27], v64, s3, v[4:5]
	v_mad_u64_u32 v[66:67], s[26:27], v66, s3, v[4:5]
	v_mad_u64_u32 v[68:69], s[26:27], v68, s3, v[4:5]
	v_mad_u64_u32 v[70:71], s[26:27], v70, s3, v[4:5]
	v_mad_u64_u32 v[72:73], s[26:27], v72, s3, v[4:5]
	v_mad_u64_u32 v[74:75], s[26:27], v74, s3, v[4:5]
	v_mad_u64_u32 v[76:77], s[26:27], v76, s3, v[4:5]
	v_mad_u64_u32 v[78:79], s[26:27], v78, s3, v[4:5]
	s_waitcnt vmcnt(15)
	ds_write_b32 v48, v80
	s_waitcnt vmcnt(14)
	ds_write_b32 v50, v81
	s_waitcnt vmcnt(13)
	ds_write_b32 v52, v82
	s_waitcnt vmcnt(12)
	ds_write_b32 v54, v83
	s_waitcnt vmcnt(11)
	ds_write_b32 v56, v84
	s_waitcnt vmcnt(10)
	ds_write_b32 v58, v85
	s_waitcnt vmcnt(9)
	ds_write_b32 v60, v86
	s_waitcnt vmcnt(8)
	ds_write_b32 v62, v87
	s_waitcnt vmcnt(7)
	ds_write_b32 v64, v88
	s_waitcnt vmcnt(6)
	ds_write_b32 v66, v89
	s_waitcnt vmcnt(5)
	ds_write_b32 v68, v90
	s_waitcnt vmcnt(4)
	ds_write_b32 v70, v91
	s_waitcnt vmcnt(3)
	ds_write_b32 v72, v8
	s_waitcnt vmcnt(2)
	ds_write_b32 v74, v92
	s_waitcnt vmcnt(1)
	ds_write_b32 v76, v93
	s_waitcnt vmcnt(0)
	ds_write_b32 v78, v94
	s_cbranch_scc1 .LBB0_25
	s_waitcnt lgkmcnt(0)
	ds_read2_b32 v[52:53], v40 offset0:33 offset1:41
	ds_read2_b32 v[54:55], v40 offset1:8
	ds_read2_b32 v[56:57], v40 offset0:66 offset1:74
	ds_read2_b32 v[58:59], v40 offset0:99 offset1:107
	ds_read2_b32 v[60:61], v40 offset0:132 offset1:140
	ds_read2_b32 v[62:63], v40 offset0:165 offset1:173
	ds_read2_b32 v[64:65], v40 offset0:198 offset1:206
	ds_read2_b32 v[66:67], v40 offset0:231 offset1:239
	s_lshl_b32 s24, s17, 1
	v_or_b32_e32 v3, s16, v5
	v_lshl_add_u64 v[36:37], v[18:19], 0, s[24:25]
	v_lshlrev_b32_e32 v8, 9, v3
	v_or_b32_e32 v3, s16, v41
	s_waitcnt lgkmcnt(6)
	v_cvt_pk_bf16_f32 v48, v54, v52
	v_lshl_add_u64 v[68:69], v[36:37], 0, v[8:9]
	v_lshlrev_b32_e32 v8, 9, v3
	s_waitcnt lgkmcnt(4)
	v_cvt_pk_bf16_f32 v49, v56, v58
	s_waitcnt lgkmcnt(2)
	v_cvt_pk_bf16_f32 v50, v60, v62
	s_waitcnt lgkmcnt(0)
	v_cvt_pk_bf16_f32 v51, v64, v66
	global_store_dwordx4 v[68:69], v[48:51], off sc1
	v_or_b32_e32 v3, s16, v42
	s_nop 0
	v_cvt_pk_bf16_f32 v48, v55, v53
	v_lshl_add_u64 v[52:53], v[36:37], 0, v[8:9]
	v_cvt_pk_bf16_f32 v49, v57, v59
	v_cvt_pk_bf16_f32 v50, v61, v63
	v_cvt_pk_bf16_f32 v51, v65, v67
	global_store_dwordx4 v[52:53], v[48:51], off sc1
	ds_read2_b32 v[52:53], v40 offset0:16 offset1:24
	ds_read2_b32 v[54:55], v40 offset0:49 offset1:57
	ds_read2_b32 v[56:57], v40 offset0:82 offset1:90
	ds_read2_b32 v[58:59], v40 offset0:115 offset1:123
	ds_read2_b32 v[60:61], v40 offset0:148 offset1:156
	ds_read2_b32 v[62:63], v40 offset0:181 offset1:189
	ds_read2_b32 v[64:65], v40 offset0:214 offset1:222
	ds_read2_b32 v[66:67], v40 offset0:247 offset1:255
	v_lshlrev_b32_e32 v8, 9, v3
	v_or_b32_e32 v3, s16, v43
	v_lshl_add_u64 v[68:69], v[36:37], 0, v[8:9]
	v_lshlrev_b32_e32 v8, 9, v3
	s_waitcnt lgkmcnt(6)
	v_cvt_pk_bf16_f32 v48, v52, v54
	s_waitcnt lgkmcnt(4)
	v_cvt_pk_bf16_f32 v49, v56, v58
	s_waitcnt lgkmcnt(2)
	v_cvt_pk_bf16_f32 v50, v60, v62
	s_waitcnt lgkmcnt(0)
	v_cvt_pk_bf16_f32 v51, v64, v66
	v_lshl_add_u64 v[36:37], v[36:37], 0, v[8:9]
	global_store_dwordx4 v[68:69], v[48:51], off sc1
	s_nop 1
	v_cvt_pk_bf16_f32 v48, v53, v55
	v_cvt_pk_bf16_f32 v49, v57, v59
	v_cvt_pk_bf16_f32 v50, v61, v63
	v_cvt_pk_bf16_f32 v51, v65, v67
	global_store_dwordx4 v[36:37], v[48:51], off sc1
	s_waitcnt lgkmcnt(0)

.LBB0_30:
	s_lshl_b32 s23, s18, 1
	s_lshl_b32 s24, s19, 1
	v_or_b32_e32 v8, s24, v38
	s_add_i32 s34, s23, 4
	s_add_i32 s35, s24, 4
	v_mov_b32_e32 v51, v9
	s_add_i32 s41, s24, 8
	v_lshlrev_b64 v[64:65], 10, v[8:9]
	v_or_b32_e32 v50, s34, v3
	v_or_b32_e32 v8, s35, v38
	v_mov_b32_e32 v49, v9
	v_or_b32_e32 v48, s23, v3
	s_add_i32 s53, s24, 12
	v_lshlrev_b64 v[50:51], 10, v[50:51]
	v_lshlrev_b64 v[66:67], 10, v[8:9]
	v_or_b32_e32 v8, s41, v38
	s_add_i32 s40, s23, 8
	s_add_i32 s52, s23, 12
	s_add_i32 s55, s24, 16
	v_lshlrev_b64 v[48:49], 10, v[48:49]
	v_lshl_add_u64 v[64:65], v[36:37], 0, v[64:65]
	v_lshl_add_u64 v[50:51], v[36:37], 0, v[50:51]
	v_lshlrev_b64 v[68:69], 10, v[8:9]
	v_or_b32_e32 v8, s53, v38
	v_mov_b32_e32 v53, v9
	v_mov_b32_e32 v55, v9
	s_add_i32 s57, s24, 20
	v_or_b32_e32 v52, s40, v3
	v_or_b32_e32 v54, s52, v3
	v_lshl_add_u64 v[48:49], v[36:37], 0, v[48:49]
	v_lshl_add_u64 v[66:67], v[36:37], 0, v[66:67]
	global_load_dword v80, v[64:65], off
	global_load_dword v81, v[48:49], off
	global_load_dword v82, v[66:67], off
	global_load_dword v83, v[50:51], off
	v_lshlrev_b64 v[50:51], 10, v[8:9]
	v_or_b32_e32 v8, s55, v38
	s_add_i32 s54, s23, 16
	s_add_i32 s56, s23, 20
	s_add_i32 s59, s24, 24
	v_lshlrev_b64 v[52:53], 10, v[52:53]
	v_lshlrev_b64 v[54:55], 10, v[54:55]
	v_lshl_add_u64 v[48:49], v[36:37], 0, v[68:69]
	v_lshl_add_u64 v[50:51], v[36:37], 0, v[50:51]
	v_lshlrev_b64 v[64:65], 10, v[8:9]
	v_or_b32_e32 v8, s57, v38
	v_mov_b32_e32 v57, v9
	v_mov_b32_e32 v59, v9
	s_add_i32 s58, s23, 24
	s_add_i32 s60, s23, 28
	s_add_i32 s61, s24, 28
	v_or_b32_e32 v56, s54, v3
	v_or_b32_e32 v58, s56, v3
	v_lshl_add_u64 v[52:53], v[36:37], 0, v[52:53]
	v_lshl_add_u64 v[54:55], v[36:37], 0, v[54:55]
	global_load_dword v84, v[48:49], off
	global_load_dword v85, v[52:53], off
	global_load_dword v86, v[50:51], off
	global_load_dword v87, v[54:55], off
	v_lshlrev_b64 v[50:51], 10, v[8:9]
	v_or_b32_e32 v8, s59, v38
	v_mov_b32_e32 v61, v9
	v_mov_b32_e32 v63, v9
	v_or_b32_e32 v60, s58, v3
	v_or_b32_e32 v62, s60, v3
	v_lshlrev_b64 v[56:57], 10, v[56:57]
	v_lshlrev_b64 v[58:59], 10, v[58:59]
	v_lshl_add_u64 v[48:49], v[36:37], 0, v[64:65]
	v_lshl_add_u64 v[50:51], v[36:37], 0, v[50:51]
	v_lshlrev_b64 v[52:53], 10, v[8:9]
	v_or_b32_e32 v8, s61, v38
	v_lshlrev_b64 v[60:61], 10, v[60:61]
	v_lshlrev_b64 v[62:63], 10, v[62:63]
	v_lshl_add_u64 v[56:57], v[36:37], 0, v[56:57]
	v_lshl_add_u64 v[58:59], v[36:37], 0, v[58:59]
	global_load_dword v88, v[48:49], off
	global_load_dword v89, v[56:57], off
	global_load_dword v90, v[50:51], off
	global_load_dword v91, v[58:59], off
	v_lshl_add_u64 v[48:49], v[36:37], 0, v[52:53]
	v_lshlrev_b64 v[50:51], 10, v[8:9]
	v_lshl_add_u64 v[60:61], v[36:37], 0, v[60:61]
	v_lshl_add_u64 v[62:63], v[36:37], 0, v[62:63]
	v_lshl_add_u64 v[50:51], v[36:37], 0, v[50:51]
	global_load_dword v8, v[48:49], off
	global_load_dword v92, v[60:61], off
	global_load_dword v93, v[50:51], off
	global_load_dword v94, v[62:63], off
	v_or_b32_e32 v50, s23, v1
	v_or_b32_e32 v48, s24, v2
	s_add_i32 s19, s19, 16
	s_add_i32 s18, s18, 16
	s_add_i32 s21, s21, -16
	v_mad_u64_u32 v[48:49], s[26:27], v48, s3, v[4:5]
	v_mad_u64_u32 v[50:51], s[26:27], v50, s3, v[4:5]
	v_or_b32_e32 v49, s34, v1
	v_or_b32_e32 v51, s35, v2
	v_or_b32_e32 v58, s40, v1
	v_or_b32_e32 v56, s41, v2
	v_or_b32_e32 v62, s52, v1
	v_or_b32_e32 v60, s53, v2
	v_or_b32_e32 v66, s54, v1
	v_or_b32_e32 v64, s55, v2
	v_or_b32_e32 v70, s56, v1
	v_or_b32_e32 v68, s57, v2
	v_or_b32_e32 v74, s58, v1
	v_or_b32_e32 v72, s59, v2
	v_or_b32_e32 v78, s60, v1
	v_or_b32_e32 v76, s61, v2
	s_cmp_lg_u32 s21, 0
	v_mad_u64_u32 v[52:53], s[26:27], v51, s3, v[4:5]
	v_mad_u64_u32 v[54:55], s[26:27], v49, s3, v[4:5]
	v_mad_u64_u32 v[56:57], s[26:27], v56, s3, v[4:5]
	v_mad_u64_u32 v[58:59], s[26:27], v58, s3, v[4:5]
	v_mad_u64_u32 v[60:61], s[26:27], v60, s3, v[4:5]
	v_mad_u64_u32 v[62:63], s[26:27], v62, s3, v[4:5]
	v_mad_u64_u32 v[64:65], s[26:27], v64, s3, v[4:5]
	v_mad_u64_u32 v[66:67], s[26:27], v66, s3, v[4:5]
	v_mad_u64_u32 v[68:69], s[26:27], v68, s3, v[4:5]
	v_mad_u64_u32 v[70:71], s[26:27], v70, s3, v[4:5]
	v_mad_u64_u32 v[72:73], s[26:27], v72, s3, v[4:5]
	v_mad_u64_u32 v[74:75], s[26:27], v74, s3, v[4:5]
	v_mad_u64_u32 v[76:77], s[26:27], v76, s3, v[4:5]
	v_mad_u64_u32 v[78:79], s[26:27], v78, s3, v[4:5]
	s_waitcnt vmcnt(15)
	ds_write_b32 v48, v80
	s_waitcnt vmcnt(14)
	ds_write_b32 v50, v81
	s_waitcnt vmcnt(13)
	ds_write_b32 v52, v82
	s_waitcnt vmcnt(12)
	ds_write_b32 v54, v83
	s_waitcnt vmcnt(11)
	ds_write_b32 v56, v84
	s_waitcnt vmcnt(10)
	ds_write_b32 v58, v85
	s_waitcnt vmcnt(9)
	ds_write_b32 v60, v86
	s_waitcnt vmcnt(8)
	ds_write_b32 v62, v87
	s_waitcnt vmcnt(7)
	ds_write_b32 v64, v88
	s_waitcnt vmcnt(6)
	ds_write_b32 v66, v89
	s_waitcnt vmcnt(5)
	ds_write_b32 v68, v90
	s_waitcnt vmcnt(4)
	ds_write_b32 v70, v91
	s_waitcnt vmcnt(3)
	ds_write_b32 v72, v8
	s_waitcnt vmcnt(2)
	ds_write_b32 v74, v92
	s_waitcnt vmcnt(1)
	ds_write_b32 v76, v93
	s_waitcnt vmcnt(0)
	ds_write_b32 v78, v94
	s_cbranch_scc1 .LBB0_30
	s_waitcnt lgkmcnt(0)
	ds_read2_b32 v[52:53], v40 offset0:33 offset1:41
	ds_read2_b32 v[54:55], v40 offset1:8
	ds_read2_b32 v[56:57], v40 offset0:66 offset1:74
	ds_read2_b32 v[58:59], v40 offset0:99 offset1:107
	ds_read2_b32 v[60:61], v40 offset0:132 offset1:140
	ds_read2_b32 v[62:63], v40 offset0:165 offset1:173
	ds_read2_b32 v[64:65], v40 offset0:198 offset1:206
	ds_read2_b32 v[66:67], v40 offset0:231 offset1:239
	s_lshl_b32 s24, s17, 1
	v_or_b32_e32 v3, s16, v5
	v_lshl_add_u64 v[36:37], v[22:23], 0, s[24:25]
	v_lshlrev_b32_e32 v8, 12, v3
	v_or_b32_e32 v3, s16, v41
	s_waitcnt lgkmcnt(6)
	v_cvt_pk_bf16_f32 v48, v54, v52
	v_lshl_add_u64 v[68:69], v[36:37], 0, v[8:9]
	v_lshlrev_b32_e32 v8, 12, v3
	s_waitcnt lgkmcnt(4)
	v_cvt_pk_bf16_f32 v49, v56, v58
	s_waitcnt lgkmcnt(2)
	v_cvt_pk_bf16_f32 v50, v60, v62
	s_waitcnt lgkmcnt(0)
	v_cvt_pk_bf16_f32 v51, v64, v66
	global_store_dwordx4 v[68:69], v[48:51], off sc1
	v_or_b32_e32 v3, s16, v42
	s_nop 0
	v_cvt_pk_bf16_f32 v48, v55, v53
	v_lshl_add_u64 v[52:53], v[36:37], 0, v[8:9]
	v_cvt_pk_bf16_f32 v49, v57, v59
	v_cvt_pk_bf16_f32 v50, v61, v63
	v_cvt_pk_bf16_f32 v51, v65, v67
	global_store_dwordx4 v[52:53], v[48:51], off sc1
	ds_read2_b32 v[52:53], v40 offset0:16 offset1:24
	ds_read2_b32 v[54:55], v40 offset0:49 offset1:57
	ds_read2_b32 v[56:57], v40 offset0:82 offset1:90
	ds_read2_b32 v[58:59], v40 offset0:115 offset1:123
	ds_read2_b32 v[60:61], v40 offset0:148 offset1:156
	ds_read2_b32 v[62:63], v40 offset0:181 offset1:189
	ds_read2_b32 v[64:65], v40 offset0:214 offset1:222
	ds_read2_b32 v[66:67], v40 offset0:247 offset1:255
	v_lshlrev_b32_e32 v8, 12, v3
	v_or_b32_e32 v3, s16, v43
	v_lshl_add_u64 v[68:69], v[36:37], 0, v[8:9]
	v_lshlrev_b32_e32 v8, 12, v3
	s_waitcnt lgkmcnt(6)
	v_cvt_pk_bf16_f32 v48, v52, v54
	s_waitcnt lgkmcnt(4)
	v_cvt_pk_bf16_f32 v49, v56, v58
	s_waitcnt lgkmcnt(2)
	v_cvt_pk_bf16_f32 v50, v60, v62
	s_waitcnt lgkmcnt(0)
	v_cvt_pk_bf16_f32 v51, v64, v66
	v_lshl_add_u64 v[36:37], v[36:37], 0, v[8:9]
	global_store_dwordx4 v[68:69], v[48:51], off sc1
	s_nop 1
	v_cvt_pk_bf16_f32 v48, v53, v55
	v_cvt_pk_bf16_f32 v49, v57, v59
	v_cvt_pk_bf16_f32 v50, v61, v63
	v_cvt_pk_bf16_f32 v51, v65, v67
	global_store_dwordx4 v[36:37], v[48:51], off sc1
	s_waitcnt lgkmcnt(0)

.LBB0_35:
	s_lshl_b32 s23, s18, 1
	s_lshl_b32 s24, s19, 1
	v_or_b32_e32 v8, s24, v38
	s_add_i32 s34, s23, 4
	s_add_i32 s35, s24, 4
	v_mov_b32_e32 v51, v9
	s_add_i32 s41, s24, 8
	v_lshlrev_b64 v[64:65], 10, v[8:9]
	v_or_b32_e32 v50, s34, v3
	v_or_b32_e32 v8, s35, v38
	v_mov_b32_e32 v49, v9
	v_or_b32_e32 v48, s23, v3
	s_add_i32 s53, s24, 12
	v_lshlrev_b64 v[50:51], 10, v[50:51]
	v_lshlrev_b64 v[66:67], 10, v[8:9]
	v_or_b32_e32 v8, s41, v38
	s_add_i32 s40, s23, 8
	s_add_i32 s52, s23, 12
	s_add_i32 s55, s24, 16
	v_lshlrev_b64 v[48:49], 10, v[48:49]
	v_lshl_add_u64 v[64:65], v[36:37], 0, v[64:65]
	v_lshl_add_u64 v[50:51], v[36:37], 0, v[50:51]
	v_lshlrev_b64 v[68:69], 10, v[8:9]
	v_or_b32_e32 v8, s53, v38
	v_mov_b32_e32 v53, v9
	v_mov_b32_e32 v55, v9
	s_add_i32 s57, s24, 20
	v_or_b32_e32 v52, s40, v3
	v_or_b32_e32 v54, s52, v3
	v_lshl_add_u64 v[48:49], v[36:37], 0, v[48:49]
	v_lshl_add_u64 v[66:67], v[36:37], 0, v[66:67]
	global_load_dword v80, v[64:65], off
	global_load_dword v81, v[48:49], off
	global_load_dword v82, v[66:67], off
	global_load_dword v83, v[50:51], off
	v_lshlrev_b64 v[50:51], 10, v[8:9]
	v_or_b32_e32 v8, s55, v38
	s_add_i32 s54, s23, 16
	s_add_i32 s56, s23, 20
	s_add_i32 s59, s24, 24
	v_lshlrev_b64 v[52:53], 10, v[52:53]
	v_lshlrev_b64 v[54:55], 10, v[54:55]
	v_lshl_add_u64 v[48:49], v[36:37], 0, v[68:69]
	v_lshl_add_u64 v[50:51], v[36:37], 0, v[50:51]
	v_lshlrev_b64 v[64:65], 10, v[8:9]
	v_or_b32_e32 v8, s57, v38
	v_mov_b32_e32 v57, v9
	v_mov_b32_e32 v59, v9
	s_add_i32 s58, s23, 24
	s_add_i32 s60, s23, 28
	s_add_i32 s61, s24, 28
	v_or_b32_e32 v56, s54, v3
	v_or_b32_e32 v58, s56, v3
	v_lshl_add_u64 v[52:53], v[36:37], 0, v[52:53]
	v_lshl_add_u64 v[54:55], v[36:37], 0, v[54:55]
	global_load_dword v84, v[48:49], off
	global_load_dword v85, v[52:53], off
	global_load_dword v86, v[50:51], off
	global_load_dword v87, v[54:55], off
	v_lshlrev_b64 v[50:51], 10, v[8:9]
	v_or_b32_e32 v8, s59, v38
	v_mov_b32_e32 v61, v9
	v_mov_b32_e32 v63, v9
	v_or_b32_e32 v60, s58, v3
	v_or_b32_e32 v62, s60, v3
	v_lshlrev_b64 v[56:57], 10, v[56:57]
	v_lshlrev_b64 v[58:59], 10, v[58:59]
	v_lshl_add_u64 v[48:49], v[36:37], 0, v[64:65]
	v_lshl_add_u64 v[50:51], v[36:37], 0, v[50:51]
	v_lshlrev_b64 v[52:53], 10, v[8:9]
	v_or_b32_e32 v8, s61, v38
	v_lshlrev_b64 v[60:61], 10, v[60:61]
	v_lshlrev_b64 v[62:63], 10, v[62:63]
	v_lshl_add_u64 v[56:57], v[36:37], 0, v[56:57]
	v_lshl_add_u64 v[58:59], v[36:37], 0, v[58:59]
	global_load_dword v88, v[48:49], off
	global_load_dword v89, v[56:57], off
	global_load_dword v90, v[50:51], off
	global_load_dword v91, v[58:59], off
	v_lshl_add_u64 v[48:49], v[36:37], 0, v[52:53]
	v_lshlrev_b64 v[50:51], 10, v[8:9]
	v_lshl_add_u64 v[60:61], v[36:37], 0, v[60:61]
	v_lshl_add_u64 v[62:63], v[36:37], 0, v[62:63]
	v_lshl_add_u64 v[50:51], v[36:37], 0, v[50:51]
	global_load_dword v8, v[48:49], off
	global_load_dword v92, v[60:61], off
	global_load_dword v93, v[50:51], off
	global_load_dword v94, v[62:63], off
	v_or_b32_e32 v50, s23, v1
	v_or_b32_e32 v48, s24, v2
	s_add_i32 s19, s19, 16
	s_add_i32 s18, s18, 16
	s_add_i32 s21, s21, -16
	v_mad_u64_u32 v[48:49], s[26:27], v48, s3, v[4:5]
	v_mad_u64_u32 v[50:51], s[26:27], v50, s3, v[4:5]
	v_or_b32_e32 v49, s34, v1
	v_or_b32_e32 v51, s35, v2
	v_or_b32_e32 v58, s40, v1
	v_or_b32_e32 v56, s41, v2
	v_or_b32_e32 v62, s52, v1
	v_or_b32_e32 v60, s53, v2
	v_or_b32_e32 v66, s54, v1
	v_or_b32_e32 v64, s55, v2
	v_or_b32_e32 v70, s56, v1
	v_or_b32_e32 v68, s57, v2
	v_or_b32_e32 v74, s58, v1
	v_or_b32_e32 v72, s59, v2
	v_or_b32_e32 v78, s60, v1
	v_or_b32_e32 v76, s61, v2
	s_cmp_lg_u32 s21, 0
	v_mad_u64_u32 v[52:53], s[26:27], v51, s3, v[4:5]
	v_mad_u64_u32 v[54:55], s[26:27], v49, s3, v[4:5]
	v_mad_u64_u32 v[56:57], s[26:27], v56, s3, v[4:5]
	v_mad_u64_u32 v[58:59], s[26:27], v58, s3, v[4:5]
	v_mad_u64_u32 v[60:61], s[26:27], v60, s3, v[4:5]
	v_mad_u64_u32 v[62:63], s[26:27], v62, s3, v[4:5]
	v_mad_u64_u32 v[64:65], s[26:27], v64, s3, v[4:5]
	v_mad_u64_u32 v[66:67], s[26:27], v66, s3, v[4:5]
	v_mad_u64_u32 v[68:69], s[26:27], v68, s3, v[4:5]
	v_mad_u64_u32 v[70:71], s[26:27], v70, s3, v[4:5]
	v_mad_u64_u32 v[72:73], s[26:27], v72, s3, v[4:5]
	v_mad_u64_u32 v[74:75], s[26:27], v74, s3, v[4:5]
	v_mad_u64_u32 v[76:77], s[26:27], v76, s3, v[4:5]
	v_mad_u64_u32 v[78:79], s[26:27], v78, s3, v[4:5]
	s_waitcnt vmcnt(15)
	ds_write_b32 v48, v80
	s_waitcnt vmcnt(14)
	ds_write_b32 v50, v81
	s_waitcnt vmcnt(13)
	ds_write_b32 v52, v82
	s_waitcnt vmcnt(12)
	ds_write_b32 v54, v83
	s_waitcnt vmcnt(11)
	ds_write_b32 v56, v84
	s_waitcnt vmcnt(10)
	ds_write_b32 v58, v85
	s_waitcnt vmcnt(9)
	ds_write_b32 v60, v86
	s_waitcnt vmcnt(8)
	ds_write_b32 v62, v87
	s_waitcnt vmcnt(7)
	ds_write_b32 v64, v88
	s_waitcnt vmcnt(6)
	ds_write_b32 v66, v89
	s_waitcnt vmcnt(5)
	ds_write_b32 v68, v90
	s_waitcnt vmcnt(4)
	ds_write_b32 v70, v91
	s_waitcnt vmcnt(3)
	ds_write_b32 v72, v8
	s_waitcnt vmcnt(2)
	ds_write_b32 v74, v92
	s_waitcnt vmcnt(1)
	ds_write_b32 v76, v93
	s_waitcnt vmcnt(0)
	ds_write_b32 v78, v94
	s_cbranch_scc1 .LBB0_35
	s_waitcnt lgkmcnt(0)
	ds_read2_b32 v[52:53], v40 offset0:33 offset1:41
	ds_read2_b32 v[54:55], v40 offset1:8
	ds_read2_b32 v[56:57], v40 offset0:66 offset1:74
	ds_read2_b32 v[58:59], v40 offset0:99 offset1:107
	ds_read2_b32 v[60:61], v40 offset0:132 offset1:140
	ds_read2_b32 v[62:63], v40 offset0:165 offset1:173
	ds_read2_b32 v[64:65], v40 offset0:198 offset1:206
	ds_read2_b32 v[66:67], v40 offset0:231 offset1:239
	s_lshl_b32 s24, s17, 1
	v_or_b32_e32 v3, s16, v5
	v_lshl_add_u64 v[36:37], v[26:27], 0, s[24:25]
	v_lshlrev_b32_e32 v8, 12, v3
	v_or_b32_e32 v3, s16, v41
	s_waitcnt lgkmcnt(6)
	v_cvt_pk_bf16_f32 v48, v54, v52
	v_lshl_add_u64 v[68:69], v[36:37], 0, v[8:9]
	v_lshlrev_b32_e32 v8, 12, v3
	s_waitcnt lgkmcnt(4)
	v_cvt_pk_bf16_f32 v49, v56, v58
	s_waitcnt lgkmcnt(2)
	v_cvt_pk_bf16_f32 v50, v60, v62
	s_waitcnt lgkmcnt(0)
	v_cvt_pk_bf16_f32 v51, v64, v66
	global_store_dwordx4 v[68:69], v[48:51], off sc1
	v_or_b32_e32 v3, s16, v42
	s_nop 0
	v_cvt_pk_bf16_f32 v48, v55, v53
	v_lshl_add_u64 v[52:53], v[36:37], 0, v[8:9]
	v_cvt_pk_bf16_f32 v49, v57, v59
	v_cvt_pk_bf16_f32 v50, v61, v63
	v_cvt_pk_bf16_f32 v51, v65, v67
	global_store_dwordx4 v[52:53], v[48:51], off sc1
	ds_read2_b32 v[52:53], v40 offset0:16 offset1:24
	ds_read2_b32 v[54:55], v40 offset0:49 offset1:57
	ds_read2_b32 v[56:57], v40 offset0:82 offset1:90
	ds_read2_b32 v[58:59], v40 offset0:115 offset1:123
	ds_read2_b32 v[60:61], v40 offset0:148 offset1:156
	ds_read2_b32 v[62:63], v40 offset0:181 offset1:189
	ds_read2_b32 v[64:65], v40 offset0:214 offset1:222
	ds_read2_b32 v[66:67], v40 offset0:247 offset1:255
	v_lshlrev_b32_e32 v8, 12, v3
	v_or_b32_e32 v3, s16, v43
	v_lshl_add_u64 v[68:69], v[36:37], 0, v[8:9]
	v_lshlrev_b32_e32 v8, 12, v3
	s_waitcnt lgkmcnt(6)
	v_cvt_pk_bf16_f32 v48, v52, v54
	s_waitcnt lgkmcnt(4)
	v_cvt_pk_bf16_f32 v49, v56, v58
	s_waitcnt lgkmcnt(2)
	v_cvt_pk_bf16_f32 v50, v60, v62
	s_waitcnt lgkmcnt(0)
	v_cvt_pk_bf16_f32 v51, v64, v66
	v_lshl_add_u64 v[36:37], v[36:37], 0, v[8:9]
	global_store_dwordx4 v[68:69], v[48:51], off sc1
	s_nop 1
	v_cvt_pk_bf16_f32 v48, v53, v55
	v_cvt_pk_bf16_f32 v49, v57, v59
	v_cvt_pk_bf16_f32 v50, v61, v63
	v_cvt_pk_bf16_f32 v51, v65, v67
	global_store_dwordx4 v[36:37], v[48:51], off sc1
	s_waitcnt lgkmcnt(0)

.LBB0_39:
	s_lshl_b32 s23, s17, 1
	s_lshl_b32 s24, s19, 1
	v_or_b32_e32 v38, s23, v3
	v_or_b32_e32 v48, s24, v8
	s_add_i32 s34, s23, 4
	s_add_i32 s35, s24, 4
	s_add_i32 s40, s23, 8
	s_add_i32 s41, s24, 8
	s_add_i32 s52, s23, 12
	s_add_i32 s53, s24, 12
	s_add_i32 s54, s23, 16
	s_add_i32 s55, s24, 16
	s_add_i32 s56, s23, 20
	s_add_i32 s57, s24, 20
	s_add_i32 s58, s23, 24
	s_add_i32 s59, s24, 24
	s_add_i32 s60, s23, 28
	s_add_i32 s61, s24, 28
	v_mad_i64_i32 v[48:49], s[26:27], v48, s7, v[36:37]
	v_mad_i64_i32 v[50:51], s[26:27], v38, s7, v[36:37]
	v_or_b32_e32 v38, s34, v3
	v_or_b32_e32 v52, s35, v8
	v_or_b32_e32 v58, s40, v3
	v_or_b32_e32 v56, s41, v8
	v_or_b32_e32 v62, s52, v3
	v_or_b32_e32 v60, s53, v8
	v_or_b32_e32 v66, s54, v3
	v_or_b32_e32 v64, s55, v8
	v_or_b32_e32 v70, s56, v3
	v_or_b32_e32 v68, s57, v8
	v_or_b32_e32 v74, s58, v3
	v_or_b32_e32 v72, s59, v8
	v_or_b32_e32 v78, s60, v3
	v_or_b32_e32 v76, s61, v8
	v_mad_i64_i32 v[52:53], s[26:27], v52, s7, v[36:37]
	v_mad_i64_i32 v[54:55], s[26:27], v38, s7, v[36:37]
	v_mad_i64_i32 v[56:57], s[26:27], v56, s7, v[36:37]
	v_mad_i64_i32 v[58:59], s[26:27], v58, s7, v[36:37]
	v_mad_i64_i32 v[60:61], s[26:27], v60, s7, v[36:37]
	v_mad_i64_i32 v[62:63], s[26:27], v62, s7, v[36:37]
	v_mad_i64_i32 v[64:65], s[26:27], v64, s7, v[36:37]
	v_mad_i64_i32 v[66:67], s[26:27], v66, s7, v[36:37]
	v_mad_i64_i32 v[68:69], s[26:27], v68, s7, v[36:37]
	v_mad_i64_i32 v[70:71], s[26:27], v70, s7, v[36:37]
	v_mad_i64_i32 v[72:73], s[26:27], v72, s7, v[36:37]
	v_mad_i64_i32 v[74:75], s[26:27], v74, s7, v[36:37]
	v_mad_i64_i32 v[76:77], s[26:27], v76, s7, v[36:37]
	v_mad_i64_i32 v[78:79], s[26:27], v78, s7, v[36:37]
	global_load_dword v38, v[48:49], off
	global_load_dword v80, v[50:51], off
	global_load_dword v81, v[52:53], off
	global_load_dword v82, v[54:55], off
	global_load_dword v83, v[56:57], off
	global_load_dword v84, v[58:59], off
	global_load_dword v85, v[60:61], off
	global_load_dword v86, v[62:63], off
	global_load_dword v87, v[64:65], off
	global_load_dword v88, v[66:67], off
	global_load_dword v89, v[68:69], off
	global_load_dword v90, v[70:71], off
	global_load_dword v91, v[72:73], off
	global_load_dword v92, v[74:75], off
	global_load_dword v93, v[76:77], off
	global_load_dword v94, v[78:79], off
	v_or_b32_e32 v50, s23, v1
	v_or_b32_e32 v48, s24, v2
	s_add_i32 s19, s19, 16
	s_add_i32 s17, s17, 16
	s_add_i32 s21, s21, -16
	v_mad_u64_u32 v[48:49], s[26:27], v48, s3, v[4:5]
	v_mad_u64_u32 v[50:51], s[26:27], v50, s3, v[4:5]
	v_or_b32_e32 v49, s34, v1
	v_or_b32_e32 v51, s35, v2
	v_or_b32_e32 v58, s40, v1
	v_or_b32_e32 v56, s41, v2
	v_or_b32_e32 v62, s52, v1
	v_or_b32_e32 v60, s53, v2
	v_or_b32_e32 v66, s54, v1
	v_or_b32_e32 v64, s55, v2
	v_or_b32_e32 v70, s56, v1
	v_or_b32_e32 v68, s57, v2
	v_or_b32_e32 v74, s58, v1
	v_or_b32_e32 v72, s59, v2
	v_or_b32_e32 v78, s60, v1
	v_or_b32_e32 v76, s61, v2
	s_cmp_lg_u32 s21, 0
	v_mad_u64_u32 v[52:53], s[26:27], v51, s3, v[4:5]
	v_mad_u64_u32 v[54:55], s[26:27], v49, s3, v[4:5]
	v_mad_u64_u32 v[56:57], s[26:27], v56, s3, v[4:5]
	v_mad_u64_u32 v[58:59], s[26:27], v58, s3, v[4:5]
	v_mad_u64_u32 v[60:61], s[26:27], v60, s3, v[4:5]
	v_mad_u64_u32 v[62:63], s[26:27], v62, s3, v[4:5]
	v_mad_u64_u32 v[64:65], s[26:27], v64, s3, v[4:5]
	v_mad_u64_u32 v[66:67], s[26:27], v66, s3, v[4:5]
	v_mad_u64_u32 v[68:69], s[26:27], v68, s3, v[4:5]
	v_mad_u64_u32 v[70:71], s[26:27], v70, s3, v[4:5]
	v_mad_u64_u32 v[72:73], s[26:27], v72, s3, v[4:5]
	v_mad_u64_u32 v[74:75], s[26:27], v74, s3, v[4:5]
	v_mad_u64_u32 v[76:77], s[26:27], v76, s3, v[4:5]
	v_mad_u64_u32 v[78:79], s[26:27], v78, s3, v[4:5]
	s_waitcnt vmcnt(15)
	ds_write_b32 v48, v38
	s_waitcnt vmcnt(14)
	ds_write_b32 v50, v80
	s_waitcnt vmcnt(13)
	ds_write_b32 v52, v81
	s_waitcnt vmcnt(12)
	ds_write_b32 v54, v82
	s_waitcnt vmcnt(11)
	ds_write_b32 v56, v83
	s_waitcnt vmcnt(10)
	ds_write_b32 v58, v84
	s_waitcnt vmcnt(9)
	ds_write_b32 v60, v85
	s_waitcnt vmcnt(8)
	ds_write_b32 v62, v86
	s_waitcnt vmcnt(7)
	ds_write_b32 v64, v87
	s_waitcnt vmcnt(6)
	ds_write_b32 v66, v88
	s_waitcnt vmcnt(5)
	ds_write_b32 v68, v89
	s_waitcnt vmcnt(4)
	ds_write_b32 v70, v90
	s_waitcnt vmcnt(3)
	ds_write_b32 v72, v91
	s_waitcnt vmcnt(2)
	ds_write_b32 v74, v92
	s_waitcnt vmcnt(1)
	ds_write_b32 v76, v93
	s_waitcnt vmcnt(0)
	ds_write_b32 v78, v94
	s_cbranch_scc1 .LBB0_39
	s_waitcnt lgkmcnt(0)
	ds_read2_b32 v[52:53], v40 offset0:33 offset1:41
	ds_read2_b32 v[54:55], v40 offset1:8
	ds_read2_b32 v[56:57], v40 offset0:66 offset1:74
	ds_read2_b32 v[58:59], v40 offset0:99 offset1:107
	ds_read2_b32 v[60:61], v40 offset0:132 offset1:140
	ds_read2_b32 v[62:63], v40 offset0:165 offset1:173
	ds_read2_b32 v[64:65], v40 offset0:198 offset1:206
	ds_read2_b32 v[66:67], v40 offset0:231 offset1:239
	v_or_b32_e32 v68, s16, v5
	s_ashr_i32 s19, s18, 31
	v_ashrrev_i32_e32 v69, 31, v68
	v_lshl_add_u64 v[36:37], s[18:19], 1, v[30:31]
	v_lshlrev_b64 v[68:69], 11, v[68:69]
	s_waitcnt lgkmcnt(6)
	v_cvt_pk_bf16_f32 v48, v54, v52
	v_lshl_add_u64 v[68:69], v[36:37], 0, v[68:69]
	v_or_b32_e32 v52, s16, v41
	s_waitcnt lgkmcnt(4)
	v_cvt_pk_bf16_f32 v49, v56, v58
	s_waitcnt lgkmcnt(2)
	v_cvt_pk_bf16_f32 v50, v60, v62
	s_waitcnt lgkmcnt(0)
	v_cvt_pk_bf16_f32 v51, v64, v66
	global_store_dwordx4 v[68:69], v[48:51], off sc1
	v_or_b32_e32 v68, s16, v42
	v_ashrrev_i32_e32 v69, 31, v68
	v_cvt_pk_bf16_f32 v48, v55, v53
	v_ashrrev_i32_e32 v53, 31, v52
	v_lshlrev_b64 v[52:53], 11, v[52:53]
	v_lshl_add_u64 v[52:53], v[36:37], 0, v[52:53]
	v_cvt_pk_bf16_f32 v49, v57, v59
	v_cvt_pk_bf16_f32 v50, v61, v63
	v_cvt_pk_bf16_f32 v51, v65, v67
	global_store_dwordx4 v[52:53], v[48:51], off sc1
	ds_read2_b32 v[52:53], v40 offset0:16 offset1:24
	ds_read2_b32 v[54:55], v40 offset0:49 offset1:57
	ds_read2_b32 v[56:57], v40 offset0:82 offset1:90
	ds_read2_b32 v[58:59], v40 offset0:115 offset1:123
	ds_read2_b32 v[60:61], v40 offset0:148 offset1:156
	ds_read2_b32 v[62:63], v40 offset0:181 offset1:189
	ds_read2_b32 v[64:65], v40 offset0:214 offset1:222
	ds_read2_b32 v[66:67], v40 offset0:247 offset1:255
	v_lshlrev_b64 v[68:69], 11, v[68:69]
	s_waitcnt lgkmcnt(6)
	v_cvt_pk_bf16_f32 v48, v52, v54
	v_lshl_add_u64 v[68:69], v[36:37], 0, v[68:69]
	v_or_b32_e32 v52, s16, v43
	s_waitcnt lgkmcnt(4)
	v_cvt_pk_bf16_f32 v49, v56, v58
	s_waitcnt lgkmcnt(2)
	v_cvt_pk_bf16_f32 v50, v60, v62
	s_waitcnt lgkmcnt(0)
	v_cvt_pk_bf16_f32 v51, v64, v66
	global_store_dwordx4 v[68:69], v[48:51], off sc1
	s_nop 1
	v_cvt_pk_bf16_f32 v48, v53, v55
	v_ashrrev_i32_e32 v53, 31, v52
	v_lshlrev_b64 v[52:53], 11, v[52:53]
	v_lshl_add_u64 v[36:37], v[36:37], 0, v[52:53]
	v_cvt_pk_bf16_f32 v49, v57, v59
	v_cvt_pk_bf16_f32 v50, v61, v63
	v_cvt_pk_bf16_f32 v51, v65, v67
	global_store_dwordx4 v[36:37], v[48:51], off sc1
	s_waitcnt lgkmcnt(0)
	s_branch .LBB0_2

.LBB0_43:
	v_add_u32_e32 v8, s10, v8
	v_cmp_lt_i32_e32 vcc, s3, v8
	global_store_dwordx4 v[10:11], v[2:5], off sc1
	s_or_b64 s[18:19], vcc, s[18:19]
	v_lshl_add_u64 v[10:11], v[10:11], 0, s[16:17]
	s_andn2_b64 exec, exec, s[18:19]
	s_cbranch_execnz .LBB0_43

.LBB0_151:
	s_and_b32 s73, s20, 63
	s_lshl_b32 s4, s18, 12
	s_lshl_b32 s5, s73, 6
	s_or_b32 s4, s4, s5
	s_mul_hi_i32 s5, s4, 0x1800
	s_mulk_i32 s4, 0x1800
	s_add_u32 s16, s34, s4
	s_addc_u32 s17, s35, s5
	s_lshl_b64 s[4:5], s[8:9], 1
	s_add_u32 s16, s16, s4
	s_addc_u32 s17, s17, s5
	s_cmp_gt_i32 s74, 3
	s_mov_b64 s[20:21], -1
	s_cbranch_scc0 .LBB0_153
	v_lshl_add_u64 v[56:57], s[16:17], 0, v[0:1]
	v_mov_b32_e32 v3, v1
	v_lshl_add_u64 v[48:49], v[56:57], 0, v[2:3]
	global_load_dwordx4 v[28:31], v[48:49], off
	v_mov_b32_e32 v5, v1
	v_lshl_add_u64 v[32:33], v[56:57], 0, v[4:5]
	global_load_dwordx4 v[32:35], v[32:33], off
	v_mov_b32_e32 v7, v1
	v_lshl_add_u64 v[36:37], v[56:57], 0, v[6:7]
	global_load_dwordx4 v[36:39], v[36:37], off
	v_add_co_u32_e32 v40, vcc, s72, v48
	v_mov_b32_e32 v9, v1
	s_nop 0
	v_addc_co_u32_e32 v41, vcc, 0, v49, vcc
	global_load_dwordx4 v[40:43], v[40:41], off
	v_add_co_u32_e32 v44, vcc, s46, v48
	v_lshl_add_u64 v[52:53], v[56:57], 0, v[8:9]
	s_nop 0
	v_addc_co_u32_e32 v45, vcc, 0, v49, vcc
	global_load_dwordx4 v[44:47], v[44:45], off
	v_mov_b32_e32 v11, v1
	global_load_dwordx4 v[52:55], v[52:53], off
	v_add_co_u32_e32 v48, vcc, s47, v48
	v_lshl_add_u64 v[56:57], v[56:57], 0, v[10:11]
	s_nop 0
	v_addc_co_u32_e32 v49, vcc, 0, v49, vcc
	global_load_dwordx4 v[48:51], v[48:49], off
	s_add_i32 s74, s74, -4
	global_load_dwordx4 v[56:59], v[56:57], off
	s_lshl_b32 s4, s18, 2
	s_lshr_b32 s5, s74, 1
	s_add_i32 s4, s4, s5
	s_ashr_i32 s5, s4, 31
	s_lshl_b64 s[4:5], s[4:5], 20
	s_add_u32 s18, s22, s4
	s_addc_u32 s19, s23, s5
	s_lshl_b32 s4, s73, 4
	s_and_b32 s5, s70, 8
	s_or_b32 s4, s4, s5
	v_or_b32_e32 v3, s4, v15
	v_lshlrev_b32_e32 v3, 6, v3
	v_or_b32_e32 v5, v3, v16
	s_mov_b64 s[20:21], 0
	s_waitcnt vmcnt(7)
	ds_write_b16 v13, v28
	ds_write_b16_d16_hi v13, v28 offset:144
	ds_write_b16 v13, v29 offset:288
	ds_write_b16_d16_hi v13, v29 offset:432
	ds_write_b16 v13, v30 offset:576
	ds_write_b16_d16_hi v13, v30 offset:720
	ds_write_b16 v13, v31 offset:864
	ds_write_b16_d16_hi v13, v31 offset:1008
	s_waitcnt vmcnt(6)
	ds_write_b16 v13, v32 offset:64
	ds_write_b16_d16_hi v13, v32 offset:208
	ds_write_b16 v13, v33 offset:352
	ds_write_b16_d16_hi v13, v33 offset:496
	ds_write_b16 v13, v34 offset:640
	ds_write_b16_d16_hi v13, v34 offset:784
	ds_write_b16 v13, v35 offset:928
	ds_write_b16_d16_hi v13, v35 offset:1072
	s_waitcnt vmcnt(5)
	ds_write_b16 v13, v36 offset:80
	ds_write_b16_d16_hi v13, v36 offset:224
	ds_write_b16 v13, v37 offset:368
	ds_write_b16_d16_hi v13, v37 offset:512
	ds_write_b16 v13, v38 offset:656
	s_waitcnt vmcnt(4)
	ds_write_b16 v13, v40 offset:16
	ds_write_b16_d16_hi v13, v40 offset:160
	ds_write_b16 v13, v41 offset:304
	ds_write_b16_d16_hi v13, v41 offset:448
	ds_write_b16 v13, v42 offset:592
	ds_write_b16_d16_hi v13, v42 offset:736
	ds_write_b16 v13, v43 offset:880
	ds_write_b16_d16_hi v13, v43 offset:1024
	s_waitcnt vmcnt(3)
	ds_write_b16 v13, v44 offset:32
	ds_write_b16_d16_hi v13, v44 offset:176
	ds_write_b16 v13, v45 offset:320
	ds_write_b16_d16_hi v13, v45 offset:464
	ds_write_b16 v13, v46 offset:608
	ds_write_b16_d16_hi v13, v46 offset:752
	ds_write_b16 v13, v47 offset:896
	ds_write_b16_d16_hi v13, v47 offset:1040
	s_waitcnt vmcnt(1)
	ds_write_b16 v13, v48 offset:48
	ds_write_b16_d16_hi v13, v48 offset:192
	ds_write_b16 v13, v49 offset:336
	ds_write_b16_d16_hi v13, v49 offset:480
	ds_write_b16 v13, v50 offset:624
	ds_write_b16_d16_hi v13, v50 offset:768
	ds_write_b16 v13, v51 offset:912
	ds_write_b16_d16_hi v13, v51 offset:1056
	ds_write_b16_d16_hi v13, v38 offset:800
	ds_write_b16 v13, v39 offset:944
	ds_write_b16_d16_hi v13, v39 offset:1088
	ds_write_b16 v13, v52 offset:96
	ds_write_b16_d16_hi v13, v52 offset:240
	ds_write_b16 v13, v53 offset:384
	ds_write_b16_d16_hi v13, v53 offset:528
	ds_write_b16 v13, v54 offset:672
	ds_write_b16_d16_hi v13, v54 offset:816
	ds_write_b16 v13, v55 offset:960
	ds_write_b16_d16_hi v13, v55 offset:1104
	s_waitcnt vmcnt(0)
	ds_write_b16 v13, v56 offset:112
	ds_write_b16_d16_hi v13, v56 offset:256
	ds_write_b16 v13, v57 offset:400
	ds_write_b16_d16_hi v13, v57 offset:544
	ds_write_b16 v13, v58 offset:688
	ds_write_b16_d16_hi v13, v58 offset:832
	ds_write_b16 v13, v59 offset:976
	ds_write_b16_d16_hi v13, v59 offset:1120
	s_waitcnt lgkmcnt(0)
	ds_read_b128 v[28:31], v25
	v_or_b32_e32 v32, v5, v12
	v_mov_b32_e32 v33, v1
	v_lshl_add_u64 v[36:37], v[32:33], 4, s[18:19]
	ds_read_b128 v[32:35], v25 offset:1152
	s_waitcnt lgkmcnt(1)
	global_store_dwordx4 v[36:37], v[28:31], off sc1
	s_nop 1
	v_or_b32_e32 v28, v5, v14
	v_mov_b32_e32 v29, v1
	v_lshl_add_u64 v[36:37], v[28:29], 4, s[18:19]
	ds_read_b128 v[28:31], v25 offset:2304
	s_waitcnt lgkmcnt(1)
	global_store_dwordx4 v[36:37], v[32:35], off sc1
	ds_read_b128 v[32:35], v25 offset:3456
	v_or_b32_e32 v5, v3, v17
	v_lshlrev_b32_e32 v5, 4, v5
	s_waitcnt lgkmcnt(1)
	global_store_dwordx4 v5, v[28:31], s[18:19] sc1
	v_or_b32_e32 v5, v3, v19
	ds_read_b128 v[28:31], v25 offset:4608
	v_lshlrev_b32_e32 v5, 4, v5
	s_waitcnt lgkmcnt(1)
	global_store_dwordx4 v5, v[32:35], s[18:19] sc1
	ds_read_b128 v[32:35], v25 offset:5760
	v_or_b32_e32 v5, v3, v20
	v_lshlrev_b32_e32 v5, 4, v5
	s_waitcnt lgkmcnt(1)
	global_store_dwordx4 v5, v[28:31], s[18:19] sc1
	v_or_b32_e32 v5, v3, v21
	v_lshlrev_b32_e32 v5, 4, v5
	ds_read_b128 v[28:31], v25 offset:6912
	s_waitcnt lgkmcnt(1)
	global_store_dwordx4 v5, v[32:35], s[18:19] sc1
	ds_read_b128 v[32:35], v25 offset:8064
	v_or_b32_e32 v5, v3, v22
	v_or_b32_e32 v3, v3, v23
	v_lshlrev_b32_e32 v5, 4, v5
	v_lshlrev_b32_e32 v3, 4, v3
	s_waitcnt lgkmcnt(1)
	global_store_dwordx4 v5, v[28:31], s[18:19] sc1
	s_waitcnt lgkmcnt(0)
	global_store_dwordx4 v3, v[32:35], s[18:19] sc1
	s_waitcnt lgkmcnt(0)
.LBB0_153:
	s_andn2_b64 vcc, exec, s[20:21]
	s_cbranch_vccnz .LBB0_142
	v_lshl_add_u64 v[56:57], s[16:17], 0, v[0:1]
	v_mov_b32_e32 v3, v1
	v_lshl_add_u64 v[52:53], v[56:57], 0, v[2:3]
	global_load_dwordx4 v[28:31], v[52:53], off
	v_mov_b32_e32 v5, v1
	v_lshl_add_u64 v[32:33], v[56:57], 0, v[4:5]
	global_load_dwordx4 v[32:35], v[32:33], off
	v_mov_b32_e32 v7, v1
	v_lshl_add_u64 v[36:37], v[56:57], 0, v[6:7]
	global_load_dwordx4 v[36:39], v[36:37], off
	v_mov_b32_e32 v9, v1
	v_lshl_add_u64 v[40:41], v[56:57], 0, v[8:9]
	global_load_dwordx4 v[40:43], v[40:41], off
	v_add_co_u32_e32 v44, vcc, s46, v52
	v_mov_b32_e32 v11, v1
	s_nop 0
	v_addc_co_u32_e32 v45, vcc, 0, v53, vcc
	global_load_dwordx4 v[44:47], v[44:45], off
	v_add_co_u32_e32 v48, vcc, s47, v52
	v_lshl_add_u64 v[56:57], v[56:57], 0, v[10:11]
	s_nop 0
	v_addc_co_u32_e32 v49, vcc, 0, v53, vcc
	global_load_dwordx4 v[48:51], v[48:49], off
	v_add_co_u32_e32 v52, vcc, s72, v52
	global_load_dwordx4 v[56:59], v[56:57], off
	s_nop 0
	v_addc_co_u32_e32 v53, vcc, 0, v53, vcc
	global_load_dwordx4 v[52:55], v[52:53], off
	v_lshl_or_b32 v3, s73, 9, v24
	v_or_b32_e32 v5, v3, v16
	v_or_b32_e32 v7, v5, v12
	v_lshlrev_b32_e32 v7, 4, v7
	v_or_b32_e32 v5, v5, v14
	v_lshlrev_b32_e32 v5, 4, v5
	v_or_b32_e32 v3, v3, v18
	v_lshlrev_b32_e32 v3, 4, v3
	s_waitcnt vmcnt(7)
	ds_write_b16 v13, v28
	ds_write_b16_d16_hi v13, v28 offset:144
	ds_write_b16 v13, v29 offset:288
	ds_write_b16_d16_hi v13, v29 offset:432
	ds_write_b16 v13, v30 offset:576
	ds_write_b16_d16_hi v13, v30 offset:720
	ds_write_b16 v13, v31 offset:864
	ds_write_b16_d16_hi v13, v31 offset:1008
	s_waitcnt vmcnt(6)
	ds_write_b16 v13, v32 offset:64
	ds_write_b16_d16_hi v13, v32 offset:208
	ds_write_b16 v13, v33 offset:352
	ds_write_b16_d16_hi v13, v33 offset:496
	ds_write_b16 v13, v34 offset:640
	ds_write_b16_d16_hi v13, v34 offset:784
	ds_write_b16 v13, v35 offset:928
	ds_write_b16_d16_hi v13, v35 offset:1072
	s_waitcnt vmcnt(5)
	ds_write_b16 v13, v36 offset:80
	ds_write_b16_d16_hi v13, v36 offset:224
	ds_write_b16 v13, v37 offset:368
	ds_write_b16_d16_hi v13, v37 offset:512
	ds_write_b16 v13, v38 offset:656
	ds_write_b16_d16_hi v13, v38 offset:800
	ds_write_b16 v13, v39 offset:944
	ds_write_b16_d16_hi v13, v39 offset:1088
	s_waitcnt vmcnt(4)
	ds_write_b16 v13, v40 offset:96
	ds_write_b16_d16_hi v13, v40 offset:240
	ds_write_b16 v13, v41 offset:384
	ds_write_b16_d16_hi v13, v41 offset:528
	ds_write_b16 v13, v42 offset:672
	s_waitcnt vmcnt(3)
	ds_write_b16 v13, v44 offset:32
	ds_write_b16_d16_hi v13, v44 offset:176
	ds_write_b16 v13, v45 offset:320
	ds_write_b16_d16_hi v13, v45 offset:464
	ds_write_b16 v13, v46 offset:608
	ds_write_b16_d16_hi v13, v46 offset:752
	ds_write_b16 v13, v47 offset:896
	ds_write_b16_d16_hi v13, v47 offset:1040
	s_waitcnt vmcnt(2)
	ds_write_b16 v13, v48 offset:48
	ds_write_b16_d16_hi v13, v48 offset:192
	ds_write_b16 v13, v49 offset:336
	ds_write_b16_d16_hi v13, v49 offset:480
	ds_write_b16 v13, v50 offset:624
	ds_write_b16_d16_hi v13, v50 offset:768
	ds_write_b16 v13, v51 offset:912
	ds_write_b16_d16_hi v13, v51 offset:1056
	s_waitcnt vmcnt(0)
	ds_write_b16 v13, v52 offset:16
	ds_write_b16_d16_hi v13, v52 offset:160
	ds_write_b16 v13, v53 offset:304
	ds_write_b16_d16_hi v13, v53 offset:448
	ds_write_b16 v13, v54 offset:592
	ds_write_b16_d16_hi v13, v54 offset:736
	ds_write_b16 v13, v55 offset:880
	ds_write_b16_d16_hi v13, v55 offset:1024
	ds_write_b16_d16_hi v13, v42 offset:816
	ds_write_b16 v13, v43 offset:960
	ds_write_b16_d16_hi v13, v43 offset:1104
	ds_write_b16 v13, v56 offset:112
	ds_write_b16_d16_hi v13, v56 offset:256
	ds_write_b16 v13, v57 offset:400
	ds_write_b16_d16_hi v13, v57 offset:544
	ds_write_b16 v13, v58 offset:688
	ds_write_b16_d16_hi v13, v58 offset:832
	ds_write_b16 v13, v59 offset:976
	ds_write_b16_d16_hi v13, v59 offset:1120
	s_waitcnt lgkmcnt(0)
	ds_read_b128 v[28:31], v26
	ds_read_b128 v[32:35], v26 offset:1152
	s_waitcnt lgkmcnt(1)
	global_store_dwordx4 v7, v[28:31], s[10:11] sc1
	ds_read_b128 v[28:31], v26 offset:2304
	s_waitcnt lgkmcnt(1)
	global_store_dwordx4 v5, v[32:35], s[10:11] sc1
	ds_read_b128 v[32:35], v26 offset:3456
	s_waitcnt lgkmcnt(1)
	global_store_dwordx4 v7, v[28:31], s[10:11] offset:1024 sc1
	ds_read_b128 v[28:31], v26 offset:4608
	ds_read_b128 v[36:39], v26 offset:5760
	ds_read_b128 v[40:43], v26 offset:6912
	ds_read_b128 v[44:47], v26 offset:8064
	s_waitcnt lgkmcnt(4)
	global_store_dwordx4 v3, v[32:35], s[10:11] offset:1024 sc1
	s_waitcnt lgkmcnt(3)
	global_store_dwordx4 v7, v[28:31], s[10:11] offset:2048 sc1
	s_waitcnt lgkmcnt(2)
	global_store_dwordx4 v3, v[36:39], s[10:11] offset:2048 sc1
	s_waitcnt lgkmcnt(1)
	global_store_dwordx4 v7, v[40:43], s[10:11] offset:3072 sc1
	s_waitcnt lgkmcnt(0)
	global_store_dwordx4 v3, v[44:47], s[10:11] offset:3072 sc1
	s_waitcnt lgkmcnt(0)
	s_branch .LBB0_142

.LBB0_296:
	s_ashr_i32 s9, s4, 7
	s_bfe_u32 s6, s4, 0x30004
	s_lshl_b32 s4, s4, 2
	s_and_b32 s10, s4, 60
	s_add_i32 s11, s10, s78
	s_lshl_b32 s4, s6, 12
	s_lshl_b32 s5, s11, 6
	s_add_i32 s4, s5, s4
	s_bfe_u32 s0, s83, 0x30004
	s_and_b32 s1, s91, 15
	s_ashr_i32 s5, s4, 31
	s_lshl_b32 s8, s0, 12
	s_lshl_b32 s0, s0, 8
	s_lshl_b32 s1, s1, 2
	s_lshl_b64 s[4:5], s[4:5], 11
	s_add_u32 s7, s30, s4
	s_addc_u32 s12, s31, s5
	s_lshl_b32 s4, s9, 8
	s_ashr_i32 s5, s4, 31
	s_lshl_b64 s[4:5], s[4:5], 1
	s_add_u32 s4, s7, s4
	s_addc_u32 s5, s12, s5
	s_add_u32 s4, s4, s86
	s_addc_u32 s5, s5, 0
	v_lshl_add_u64 v[0:1], s[4:5], 0, v[26:27]
	s_mov_b64 s[4:5], 0x4000100
	v_lshl_add_u64 v[48:49], v[0:1], 0, s[4:5]
	v_lshl_add_u64 v[0:1], v[48:49], 0, v[28:29]
	global_load_dwordx4 v[0:3], v[0:1], off
	v_lshl_add_u64 v[4:5], v[48:49], 0, v[30:31]
	global_load_dwordx4 v[4:7], v[4:5], off
	v_lshl_add_u64 v[8:9], v[48:49], 0, v[32:33]
	global_load_dwordx4 v[8:11], v[8:9], off
	v_lshl_add_u64 v[12:13], v[48:49], 0, v[34:35]
	global_load_dwordx4 v[12:15], v[12:13], off
	v_lshl_add_u64 v[16:17], v[48:49], 0, v[36:37]
	global_load_dwordx4 v[16:19], v[16:17], off
	v_lshl_add_u64 v[20:21], v[48:49], 0, v[38:39]
	global_load_dwordx4 v[20:23], v[20:21], off
	v_lshl_add_u64 v[44:45], v[48:49], 0, v[40:41]
	global_load_dwordx4 v[44:47], v[44:45], off
	v_lshl_add_u64 v[48:49], v[48:49], 0, v[42:43]
	global_load_dwordx4 v[48:51], v[48:49], off
	s_lshl_b32 s4, s6, 2
	s_add_i32 s4, s4, s9
	s_ashr_i32 s5, s4, 31
	s_lshl_b64 s[6:7], s[4:5], 20
	s_add_u32 s6, s79, s6
	s_addc_u32 s7, s80, s7
	s_lshl_b32 s5, s92, 2
	s_and_b32 s93, s5, 4
	s_lshl_b32 s5, s4, 6
	s_or_b32 s94, s5, s10
	s_and_b32 s5, s9, 3
	s_lshl_b32 s4, s4, 10
	s_and_b32 s95, s4, 0xfffff000
	s_lshl_b32 s4, s5, 2
	s_add_u32 s24, s52, s4
	s_addc_u32 s25, s53, 0
	s_add_u32 s44, s54, s4
	s_addc_u32 s45, s55, 0
	s_lshl_b32 s4, s5, 9
	s_add_u32 s96, s14, s4
	s_addc_u32 s97, s15, 0
	s_add_u32 s46, s30, s4
	s_addc_u32 s47, s31, 0
	s_lshl_b32 s4, s9, 10
	s_add_i32 s8, s8, s4
	s_lshl_b32 s4, s9, 6
	s_add_i32 s0, s0, s4
	s_and_b32 s26, s8, 0xfffff000
	s_or_b32 s27, s0, s1
	s_lshl_b32 s16, s5, 1
	s_mov_b32 s0, s17
	s_waitcnt vmcnt(7)
	ds_write_b16 v65, v0
	ds_write_b16_d16_hi v65, v0 offset:144
	ds_write_b16 v65, v1 offset:288
	ds_write_b16_d16_hi v65, v1 offset:432
	ds_write_b16 v65, v2 offset:576
	ds_write_b16_d16_hi v65, v2 offset:720
	ds_write_b16 v65, v3 offset:864
	ds_write_b16_d16_hi v65, v3 offset:1008
	s_waitcnt vmcnt(6)
	ds_write_b16 v65, v4 offset:16
	ds_write_b16_d16_hi v65, v4 offset:160
	ds_write_b16 v65, v5 offset:304
	ds_write_b16_d16_hi v65, v5 offset:448
	ds_write_b16 v65, v6 offset:592
	ds_write_b16_d16_hi v65, v6 offset:736
	ds_write_b16 v65, v7 offset:880
	ds_write_b16_d16_hi v65, v7 offset:1024
	s_waitcnt vmcnt(5)
	ds_write_b16 v65, v8 offset:32
	ds_write_b16_d16_hi v65, v8 offset:176
	ds_write_b16 v65, v9 offset:320
	ds_write_b16_d16_hi v65, v9 offset:464
	ds_write_b16 v65, v10 offset:608
	ds_write_b16_d16_hi v65, v10 offset:752
	ds_write_b16 v65, v11 offset:896
	ds_write_b16_d16_hi v65, v11 offset:1040
	s_waitcnt vmcnt(4)
	ds_write_b16 v65, v12 offset:48
	ds_write_b16_d16_hi v65, v12 offset:192
	ds_write_b16 v65, v13 offset:336
	ds_write_b16_d16_hi v65, v13 offset:480
	ds_write_b16 v65, v14 offset:624
	ds_write_b16_d16_hi v65, v14 offset:768
	ds_write_b16 v65, v15 offset:912
	ds_write_b16_d16_hi v65, v15 offset:1056
	s_waitcnt vmcnt(3)
	ds_write_b16 v65, v16 offset:64
	ds_write_b16_d16_hi v65, v16 offset:208
	ds_write_b16 v65, v17 offset:352
	ds_write_b16_d16_hi v65, v17 offset:496
	ds_write_b16 v65, v18 offset:640
	ds_write_b16_d16_hi v65, v18 offset:784
	ds_write_b16 v65, v19 offset:928
	ds_write_b16_d16_hi v65, v19 offset:1072
	s_waitcnt vmcnt(2)
	ds_write_b16 v65, v20 offset:80
	ds_write_b16_d16_hi v65, v20 offset:224
	ds_write_b16 v65, v21 offset:368
	ds_write_b16_d16_hi v65, v21 offset:512
	ds_write_b16 v65, v22 offset:656
	ds_write_b16_d16_hi v65, v22 offset:800
	ds_write_b16 v65, v23 offset:944
	ds_write_b16_d16_hi v65, v23 offset:1088
	s_waitcnt vmcnt(1)
	ds_write_b16 v65, v44 offset:96
	ds_write_b16_d16_hi v65, v44 offset:240
	ds_write_b16 v65, v45 offset:384
	ds_write_b16_d16_hi v65, v45 offset:528
	ds_write_b16 v65, v46 offset:672
	ds_write_b16_d16_hi v65, v46 offset:816
	ds_write_b16 v65, v47 offset:960
	ds_write_b16_d16_hi v65, v47 offset:1104
	s_waitcnt vmcnt(0)
	ds_write_b16 v65, v48 offset:112
	ds_write_b16_d16_hi v65, v48 offset:256
	ds_write_b16 v65, v49 offset:400
	ds_write_b16_d16_hi v65, v49 offset:544
	ds_write_b16 v65, v50 offset:688
	ds_write_b16_d16_hi v65, v50 offset:832
	ds_write_b16 v65, v51 offset:976
	ds_write_b16_d16_hi v65, v51 offset:1120
	s_waitcnt lgkmcnt(0)
	v_lshl_or_b32 v10, s11, 10, v74
	ds_read_b128 v[0:3], v75
	v_or_b32_e32 v11, v10, v67
	v_or_b32_e32 v4, v11, v64
	v_ashrrev_i32_e32 v5, 31, v4
	v_lshl_add_u64 v[8:9], v[4:5], 4, s[6:7]
	ds_read_b128 v[4:7], v75 offset:1152
	s_waitcnt lgkmcnt(1)
	global_store_dwordx4 v[8:9], v[0:3], off sc1
	s_nop 1
	v_or_b32_e32 v0, v11, v66
	v_ashrrev_i32_e32 v1, 31, v0
	v_lshl_add_u64 v[0:1], v[0:1], 4, s[6:7]
	s_waitcnt lgkmcnt(0)
	global_store_dwordx4 v[0:1], v[4:7], off sc1
	ds_read_b128 v[0:3], v75 offset:2304
	s_nop 0
	v_or_b32_e32 v4, v10, v68
	v_ashrrev_i32_e32 v5, 31, v4
	v_lshl_add_u64 v[8:9], v[4:5], 4, s[6:7]
	ds_read_b128 v[4:7], v75 offset:3456
	s_waitcnt lgkmcnt(1)
	global_store_dwordx4 v[8:9], v[0:3], off sc1
	s_nop 1
	v_or_b32_e32 v0, v10, v69
	v_ashrrev_i32_e32 v1, 31, v0
	v_lshl_add_u64 v[0:1], v[0:1], 4, s[6:7]
	s_waitcnt lgkmcnt(0)
	global_store_dwordx4 v[0:1], v[4:7], off sc1
	ds_read_b128 v[0:3], v75 offset:4608
	s_nop 0
	v_or_b32_e32 v4, v10, v70
	v_ashrrev_i32_e32 v5, 31, v4
	v_lshl_add_u64 v[8:9], v[4:5], 4, s[6:7]
	ds_read_b128 v[4:7], v75 offset:5760
	s_waitcnt lgkmcnt(1)
	global_store_dwordx4 v[8:9], v[0:3], off sc1
	s_nop 1
	v_or_b32_e32 v0, v10, v71
	v_ashrrev_i32_e32 v1, 31, v0
	v_lshl_add_u64 v[0:1], v[0:1], 4, s[6:7]
	s_waitcnt lgkmcnt(0)
	global_store_dwordx4 v[0:1], v[4:7], off sc1
	ds_read_b128 v[0:3], v75 offset:6912
	s_nop 0
	v_or_b32_e32 v4, v10, v72
	v_ashrrev_i32_e32 v5, 31, v4
	v_lshl_add_u64 v[8:9], v[4:5], 4, s[6:7]
	ds_read_b128 v[4:7], v75 offset:8064
	s_waitcnt lgkmcnt(1)
	global_store_dwordx4 v[8:9], v[0:3], off sc1
	s_nop 1
	v_or_b32_e32 v0, v10, v73
	v_ashrrev_i32_e32 v1, 31, v0
	v_lshl_add_u64 v[0:1], v[0:1], 4, s[6:7]
	s_waitcnt lgkmcnt(0)
	global_store_dwordx4 v[0:1], v[4:7], off sc1
	s_waitcnt lgkmcnt(0)
	s_branch .LBB0_298

.LBB0_300:
	s_nop 4
	v_sub_f32_e32 v0, v91, v112
	v_mul_f32_e32 v0, 0x3fb8aa3b, v0
	v_sub_f32_e32 v1, v92, v112
	v_exp_f32_e32 v0, v0
	v_mul_f32_e32 v1, 0x3fb8aa3b, v1
	v_sub_f32_e32 v2, v93, v112
	v_exp_f32_e32 v1, v1
	v_mul_f32_e32 v2, 0x3fb8aa3b, v2
	v_sub_f32_e32 v3, v94, v112
	v_exp_f32_e32 v2, v2
	v_mul_f32_e32 v3, 0x3fb8aa3b, v3
	v_sub_f32_e32 v4, v95, v112
	v_exp_f32_e32 v3, v3
	v_mul_f32_e32 v4, 0x3fb8aa3b, v4
	v_sub_f32_e32 v5, v96, v112
	v_mul_f32_e32 v0, v0, v20
	v_cmp_le_i32_e32 vcc, v90, v99
	v_exp_f32_e32 v4, v4
	v_mul_f32_e32 v5, 0x3fb8aa3b, v5
	v_sub_f32_e32 v6, v97, v112
	v_cndmask_b32_e32 v0, 0, v0, vcc
	v_mul_f32_e32 v1, v1, v21
	v_cmp_le_i32_e32 vcc, v105, v99
	v_exp_f32_e32 v5, v5
	v_mul_f32_e32 v6, 0x3fb8aa3b, v6
	v_sub_f32_e32 v7, v98, v112
	v_cndmask_b32_e32 v1, 0, v1, vcc
	v_mul_f32_e32 v2, v2, v22
	v_cmp_le_i32_e32 vcc, v106, v99
	v_exp_f32_e32 v6, v6
	v_mul_f32_e32 v7, 0x3fb8aa3b, v7
	v_cndmask_b32_e32 v2, 0, v2, vcc
	v_mul_f32_e32 v3, v3, v23
	v_cmp_le_i32_e32 vcc, v107, v99
	v_exp_f32_e32 v7, v7
	v_mul_f32_e32 v4, v4, v8
	v_cndmask_b32_e32 v3, 0, v3, vcc
	v_cmp_le_i32_e32 vcc, v108, v99
	s_add_i32 s1, s1, 1
	v_mul_f32_e32 v5, v5, v9
	v_cndmask_b32_e32 v4, 0, v4, vcc
	v_cmp_le_i32_e32 vcc, v109, v99
	s_add_u32 s8, s8, 0x8000
	v_mul_f32_e32 v6, v6, v10
	v_cndmask_b32_e32 v5, 0, v5, vcc
	v_cmp_le_i32_e32 vcc, v110, v99
	s_addc_u32 s9, s9, 0
	v_mul_f32_e32 v7, v7, v11
	v_cndmask_b32_e32 v6, 0, v6, vcc
	v_cmp_le_i32_e32 vcc, v111, v99
	v_add_u32_e32 v60, 0x80, v60
	v_add_u32_e32 v44, 0x100, v44
	v_add_u32_e32 v99, 16, v99
	s_cmp_lg_u32 s8, 0x20000
	v_add_u32_e32 v24, 64, v24
	v_cndmask_b32_e32 v7, 0, v7, vcc
	v_cvt_pk_bf16_f32 v0, v0, v1
	v_cvt_pk_bf16_f32 v1, v2, v3
	v_cvt_pk_bf16_f32 v2, v4, v5
	v_cvt_pk_bf16_f32 v3, v6, v7
	global_store_dwordx4 v[62:63], v[0:3], off offset:1024 sc1
	s_cbranch_scc0 .LBB0_297
.LBB0_301:
	s_nop 0
	v_lshl_add_u64 v[0:1], v[56:57], 0, s[8:9]
	v_add_co_u32_e32 v16, vcc, 0x4000000, v0
	v_lshl_add_u64 v[4:5], v[58:59], 0, s[8:9]
	s_nop 0
	v_addc_co_u32_e32 v17, vcc, 0, v1, vcc
	v_add_co_u32_e32 v20, vcc, 0x4000000, v4
	global_load_dwordx4 v[0:3], v[16:17], off
	s_nop 0
	v_addc_co_u32_e32 v21, vcc, 0, v5, vcc
	global_load_dwordx4 v[4:7], v[16:17], off offset:64
	global_load_dwordx4 v[12:15], v[16:17], off offset:128
	global_load_dwordx4 v[166:169], v[16:17], off offset:192
	global_load_dwordx2 v[170:171], v[20:21], off
	global_load_dwordx2 v[172:173], v[20:21], off offset:32
	global_load_dwordx2 v[174:175], v[20:21], off offset:64
	global_load_dwordx2 v[176:177], v[20:21], off offset:96
	global_load_dwordx2 v[178:179], v[20:21], off offset:128
	global_load_dwordx2 v[180:181], v[20:21], off offset:160
	global_load_dwordx2 v[182:183], v[20:21], off offset:192
	global_load_dwordx2 v[184:185], v[20:21], off offset:224
	v_ashrrev_i32_e32 v45, 31, v44
	v_lshl_add_u64 v[22:23], v[44:45], 4, s[6:7]
	ds_bpermute_b32 v112, v24, v81
	v_cmp_le_i32_e32 vcc, v46, v99
	s_cmp_gt_u32 s1, 1
	s_cselect_b64 s[10:11], -1, 0
	s_cmp_lt_u32 s1, 2
	s_waitcnt lgkmcnt(0)
	v_sub_f32_e32 v61, v86, v112
	v_mul_f32_e32 v61, 0x3fb8aa3b, v61
	v_exp_f32_e32 v61, v61
	s_waitcnt vmcnt(0)
	global_store_dwordx4 v[22:23], v[170:173], off sc1
	global_store_dwordx4 v[22:23], v[174:177], off offset:1024 sc1
	global_store_dwordx4 v[22:23], v[178:181], off offset:2048 sc1
	global_store_dwordx4 v[22:23], v[182:185], off offset:3072 sc1
	v_mov_b32_e32 v16, v166
	v_mov_b32_e32 v17, v167
	v_mov_b32_e32 v18, v168
	v_mov_b32_e32 v19, v169
	v_mfma_f32_16x16x32_bf16 v[8:11], v[186:189], v[0:3], 0
	v_mfma_f32_16x16x32_bf16 v[8:11], v[190:193], v[4:7], v[8:11]
	v_mfma_f32_16x16x32_bf16 v[8:11], v[194:197], v[12:15], v[8:11]
	v_mfma_f32_16x16x32_bf16 v[8:11], v[198:201], v[16:19], v[8:11]
	v_sub_f32_e32 v20, v82, v112
	v_mul_f32_e32 v20, 0x3fb8aa3b, v20
	v_exp_f32_e32 v20, v20
	s_nop 4
	v_mul_f32_e32 v20, v20, v8
	v_cndmask_b32_e32 v45, 0, v20, vcc
	v_sub_f32_e32 v20, v83, v112
	v_mul_f32_e32 v20, 0x3fb8aa3b, v20
	v_exp_f32_e32 v20, v20
	v_cmp_lt_i32_e32 vcc, v46, v99
	v_mov_b32_e32 v8, 0
	v_mul_f32_e32 v9, v20, v9
	v_sub_f32_e32 v20, v84, v112
	v_mul_f32_e32 v20, 0x3fb8aa3b, v20
	v_exp_f32_e32 v20, v20
	v_cndmask_b32_e32 v9, 0, v9, vcc
	v_cmp_le_i32_e32 vcc, v47, v99
	v_mul_f32_e32 v10, v20, v10
	v_sub_f32_e32 v20, v85, v112
	v_mul_f32_e32 v20, 0x3fb8aa3b, v20
	v_exp_f32_e32 v20, v20
	v_cndmask_b32_e32 v10, 0, v10, vcc
	v_cmp_le_i32_e32 vcc, v100, v99
	v_mul_f32_e32 v11, v20, v11
	v_cndmask_b32_e32 v11, 0, v11, vcc
	v_cmp_le_i32_e32 vcc, v101, v99
	v_mfma_f32_16x16x32_bf16 v[20:23], v[202:205], v[0:3], 0
	v_mfma_f32_16x16x32_bf16 v[20:23], v[206:209], v[4:7], v[20:23]
	v_mfma_f32_16x16x32_bf16 v[20:23], v[210:213], v[12:15], v[20:23]
	v_mfma_f32_16x16x32_bf16 v[20:23], v[214:217], v[16:19], v[20:23]
	s_nop 7
	v_mul_f32_e32 v20, v61, v20
	v_cndmask_b32_e32 v61, 0, v20, vcc
	v_sub_f32_e32 v20, v87, v112
	v_mul_f32_e32 v20, 0x3fb8aa3b, v20
	v_exp_f32_e32 v20, v20
	v_cmp_le_i32_e32 vcc, v102, v99
	v_mul_f32_e32 v20, v20, v21
	s_nop 0
	v_cndmask_b32_e32 v62, 0, v20, vcc
	v_sub_f32_e32 v20, v88, v112
	v_mul_f32_e32 v20, 0x3fb8aa3b, v20
	v_exp_f32_e32 v20, v20
	v_cmp_le_i32_e32 vcc, v103, v99
	v_cvt_pk_bf16_f32 v21, v10, v11
	v_mul_f32_e32 v20, v20, v22
	s_nop 0
	v_cndmask_b32_e32 v63, 0, v20, vcc
	v_sub_f32_e32 v20, v89, v112
	v_mul_f32_e32 v20, 0x3fb8aa3b, v20
	v_exp_f32_e32 v20, v20
	v_cmp_le_i32_e32 vcc, v104, v99
	v_cvt_pk_bf16_f32 v22, v61, v62
	v_ashrrev_i32_e32 v61, 31, v60
	v_mul_f32_e32 v20, v20, v23
	v_cndmask_b32_e32 v23, 0, v20, vcc
	v_cvt_pk_bf16_f32 v20, v45, v9
	v_cvt_pk_bf16_f32 v23, v63, v23
	v_lshl_add_u64 v[62:63], v[60:61], 4, s[4:5]
	global_store_dwordx4 v[62:63], v[20:23], off sc1
	s_nop 1
	v_mov_b32_e32 v20, 0
	v_mov_b32_e32 v21, 0
	v_mov_b32_e32 v22, 0
	v_mov_b32_e32 v23, 0
	s_cbranch_scc1 .LBB0_303
	v_mfma_f32_16x16x32_bf16 v[20:23], v[218:221], v[0:3], 0
	v_mfma_f32_16x16x32_bf16 v[20:23], v[222:225], v[4:7], v[20:23]
	v_mfma_f32_16x16x32_bf16 v[20:23], v[226:229], v[12:15], v[20:23]
	v_mfma_f32_16x16x32_bf16 v[20:23], v[230:233], v[16:19], v[20:23]

.LBB0_334:
	s_waitcnt vmcnt(19)
	v_mfma_f32_16x16x32_bf16 v[96:99], v[128:131], v[96:99], 0
	v_max_f32_e32 v125, v215, v215
	v_max_f32_e32 v126, v210, v210
	v_max_f32_e32 v218, v126, v125
	s_waitcnt vmcnt(16)
	v_mfma_f32_16x16x32_bf16 v[96:99], v[140:143], v[120:123], v[96:99]
	v_sub_f32_e32 v125, v210, v218
	v_mul_f32_e32 v125, 0x3fb8aa3b, v125
	v_add_f32_e32 v124, v124, v218
	v_mfma_f32_16x16x32_bf16 v[96:99], v[144:147], v[116:119], v[96:99]
	ds_bpermute_b32 v116, v190, v218
	ds_bpermute_b32 v117, v190, v215
	v_exp_f32_e32 v219, v125
	v_mul_f32_e32 v120, 0xbfb8aa3b, v124
	v_exp_f32_e32 v220, v120
	s_waitcnt vmcnt(0)
	v_mfma_f32_16x16x32_bf16 v[92:95], v[52:55], v[92:95], 0
	s_and_b64 vcc, exec, s[10:11]
	s_mov_b64 s[48:49], -1
	v_mfma_f32_16x16x32_bf16 v[112:115], v[148:151], v[112:115], v[96:99]
	s_nop 2
	ds_bpermute_b32 v98, v190, v219
	s_waitcnt lgkmcnt(1)
	v_sub_f32_e32 v97, v117, v116
	v_mul_f32_e32 v97, 0x3fb8aa3b, v97
	ds_bpermute_b32 v96, v190, v220
	v_exp_f32_e32 v116, v97
	v_mfma_f32_16x16x32_bf16 v[84:87], v[32:35], v[84:87], v[92:95]
	s_waitcnt lgkmcnt(1)
	v_pk_mul_f32 v[114:115], v[114:115], v[98:99] op_sel_hi:[1,0]
	s_nop 0
	v_pk_mul_f32 v[92:93], v[112:113], v[98:99] op_sel_hi:[1,0]
	s_nop 3
	v_pk_fma_f32 v[86:87], v[116:117], v[86:87], v[114:115] op_sel_hi:[0,1,1]
	v_pk_fma_f32 v[84:85], v[116:117], v[84:85], v[92:93] op_sel_hi:[0,1,1]
	s_cbranch_vccnz .LBB0_336
	v_lshl_add_u64 v[92:93], v[170:171], 0, s[44:45]
	s_mov_b64 s[48:49], 0
	global_store_dwordx4 v[92:93], v[84:87], off sc1

.LBB0_340:
	v_mfma_f32_16x16x32_bf16 v[76:79], v[128:131], v[76:79], 0
	s_and_b64 vcc, exec, s[10:11]
	s_mov_b64 s[48:49], -1
	v_mfma_f32_16x16x32_bf16 v[76:79], v[140:143], v[80:83], v[76:79]
	ds_bpermute_b32 v80, v191, v218
	v_mfma_f32_16x16x32_bf16 v[74:77], v[144:147], v[72:75], v[76:79]
	ds_bpermute_b32 v73, v191, v215
	ds_bpermute_b32 v72, v191, v220
	s_waitcnt lgkmcnt(1)
	v_sub_f32_e32 v73, v73, v80
	v_mfma_f32_16x16x32_bf16 v[64:67], v[52:55], v[64:67], 0
	v_mul_f32_e32 v73, 0x3fb8aa3b, v73
	v_mfma_f32_16x16x32_bf16 v[68:71], v[148:151], v[68:71], v[74:77]
	s_nop 2
	ds_bpermute_b32 v74, v191, v219
	v_exp_f32_e32 v76, v73
	v_mfma_f32_16x16x32_bf16 v[48:51], v[32:35], v[48:51], v[64:67]
	s_waitcnt lgkmcnt(0)
	s_nop 0
	v_pk_mul_f32 v[70:71], v[70:71], v[74:75] op_sel_hi:[1,0]
	v_pk_mul_f32 v[68:69], v[68:69], v[74:75] op_sel_hi:[1,0]
	s_nop 3
	v_pk_fma_f32 v[48:49], v[76:77], v[48:49], v[68:69] op_sel_hi:[0,1,1]
	v_pk_fma_f32 v[50:51], v[76:77], v[50:51], v[70:71] op_sel_hi:[0,1,1]
	s_cbranch_vccnz .LBB0_342
	v_lshl_add_u64 v[64:65], v[168:169], 0, s[44:45]
	s_mov_b64 s[48:49], 0
	global_store_dwordx4 v[64:65], v[48:51], off sc1

.LBB0_346:
	v_add_co_u32_e32 v48, vcc, 0x182e0000, v178
	v_mfma_f32_16x16x32_bf16 v[222:225], v[128:131], v[40:43], 0
	s_nop 0
	v_addc_co_u32_e32 v49, vcc, 0, v179, vcc
	global_load_dwordx4 v[124:127], v[48:49], off offset:2048
	global_load_dwordx4 v[120:123], v[48:49], off offset:3072
	v_add_co_u32_e32 v48, vcc, 0x182e1000, v178
	v_mfma_f32_16x16x32_bf16 v[36:39], v[140:143], v[36:39], v[222:225]
	s_nop 0
	v_addc_co_u32_e32 v49, vcc, 0, v179, vcc
	global_load_dwordx4 v[112:115], v[48:49], off
	global_load_dwordx4 v[116:119], v[48:49], off offset:1024
	global_load_dwordx4 v[92:95], v[48:49], off offset:2048
	global_load_dwordx4 v[96:99], v[48:49], off offset:3072
	v_add_co_u32_e32 v48, vcc, 0x182e2000, v178
	v_mfma_f32_16x16x32_bf16 v[222:225], v[144:147], v[44:47], v[36:39]
	s_nop 0
	v_addc_co_u32_e32 v49, vcc, 0, v179, vcc
	v_add_co_u32_e32 v226, vcc, 0x182e3000, v178
	global_load_dwordx4 v[80:83], v[48:49], off
	global_load_dwordx4 v[84:87], v[48:49], off offset:1024
	global_load_dwordx4 v[72:75], v[48:49], off offset:2048
	global_load_dwordx4 v[76:79], v[48:49], off offset:3072
	v_addc_co_u32_e32 v227, vcc, 0, v179, vcc
	v_add_co_u32_e32 v178, vcc, 0x182e4000, v178
	global_load_dwordx4 v[68:71], v[226:227], off
	global_load_dwordx4 v[64:67], v[226:227], off offset:1024
	v_addc_co_u32_e32 v179, vcc, 0, v179, vcc
	global_load_dwordx4 v[48:51], v[226:227], off offset:2048
	global_load_dwordx4 v[40:43], v[226:227], off offset:3072
	global_load_dwordx4 v[44:47], v[178:179], off
	global_load_dwordx4 v[36:39], v[178:179], off offset:1024
	ds_bpermute_b32 v178, v192, v218
	v_mfma_f32_16x16x32_bf16 v[222:225], v[148:151], v[152:155], v[222:225]
	ds_bpermute_b32 v153, v192, v215
	ds_bpermute_b32 v154, v192, v219
	ds_bpermute_b32 v152, v192, v220
	v_mfma_f32_16x16x32_bf16 v[132:135], v[52:55], v[132:135], 0
	s_and_b64 vcc, exec, s[10:11]
	s_waitcnt lgkmcnt(2)
	v_sub_f32_e32 v153, v153, v178
	v_mul_f32_e32 v153, 0x3fb8aa3b, v153
	v_exp_f32_e32 v178, v153
	v_mfma_f32_16x16x32_bf16 v[132:135], v[32:35], v[136:139], v[132:135]
	s_waitcnt lgkmcnt(1)
	v_pk_mul_f32 v[136:137], v[224:225], v[154:155] op_sel_hi:[1,0]
	v_pk_mul_f32 v[138:139], v[222:223], v[154:155] op_sel_hi:[1,0]
	s_mov_b64 s[48:49], -1
	s_nop 3
	v_pk_fma_f32 v[132:133], v[178:179], v[132:133], v[138:139] op_sel_hi:[0,1,1]
	v_pk_fma_f32 v[134:135], v[178:179], v[134:135], v[136:137] op_sel_hi:[0,1,1]
	s_cbranch_vccnz .LBB0_348
	v_lshl_add_u64 v[136:137], v[166:167], 0, s[44:45]
	s_mov_b64 s[48:49], 0
	global_store_dwordx4 v[136:137], v[132:135], off sc1

.LBB0_352:
	v_mfma_f32_16x16x32_bf16 v[100:103], v[128:131], v[100:103], 0
	s_and_b64 vcc, exec, s[10:11]
	s_mov_b64 s[48:49], -1
	v_mfma_f32_16x16x32_bf16 v[100:103], v[140:143], v[108:111], v[100:103]
	ds_bpermute_b32 v108, v193, v218
	v_mfma_f32_16x16x32_bf16 v[102:105], v[144:147], v[104:107], v[100:103]
	v_mfma_f32_16x16x32_bf16 v[56:59], v[52:55], v[56:59], 0
	s_nop 4
	ds_bpermute_b32 v101, v193, v215
	ds_bpermute_b32 v100, v193, v220
	s_waitcnt lgkmcnt(1)
	v_sub_f32_e32 v101, v101, v108
	v_mfma_f32_16x16x32_bf16 v[88:91], v[148:151], v[88:91], v[102:105]
	v_mul_f32_e32 v101, 0x3fb8aa3b, v101
	s_nop 1
	ds_bpermute_b32 v102, v193, v219
	v_exp_f32_e32 v104, v101
	v_mfma_f32_16x16x32_bf16 v[56:59], v[32:35], v[60:63], v[56:59]
	s_waitcnt lgkmcnt(0)
	s_nop 0
	v_pk_mul_f32 v[90:91], v[90:91], v[102:103] op_sel_hi:[1,0]
	v_pk_mul_f32 v[88:89], v[88:89], v[102:103] op_sel_hi:[1,0]
	s_nop 3
	v_pk_fma_f32 v[56:57], v[104:105], v[56:57], v[88:89] op_sel_hi:[0,1,1]
	v_pk_fma_f32 v[58:59], v[104:105], v[58:59], v[90:91] op_sel_hi:[0,1,1]
	s_cbranch_vccnz .LBB0_354
	v_lshl_add_u64 v[60:61], v[164:165], 0, s[44:45]
	s_mov_b64 s[48:49], 0
	global_store_dwordx4 v[60:61], v[56:59], off sc1

.Lft_noks:
	v_mul_u32_u24_e32 v5, 33, v1
	v_lshl_add_u32 v5, v0, 2, v5
	v_lshl_add_u32 v5, v5, 2, s79
	v_mul_u32_u24_e32 v6, 0x108, v0
	v_add_u32_e32 v6, v6, v1
	v_lshl_add_u32 v6, v6, 2, s79
	s_waitcnt vmcnt(0)
	ds_write_b32 v5, v16 offset:0
	ds_write_b32 v5, v17 offset:4
	ds_write_b32 v5, v18 offset:8
	ds_write_b32 v5, v19 offset:12
	ds_write_b32 v5, v20 offset:1056
	ds_write_b32 v5, v21 offset:1060
	ds_write_b32 v5, v22 offset:1064
	ds_write_b32 v5, v23 offset:1068
	ds_write_b32 v5, v24 offset:2112
	ds_write_b32 v5, v25 offset:2116
	ds_write_b32 v5, v26 offset:2120
	ds_write_b32 v5, v27 offset:2124
	ds_write_b32 v5, v28 offset:3168
	ds_write_b32 v5, v29 offset:3172
	ds_write_b32 v5, v30 offset:3176
	ds_write_b32 v5, v31 offset:3180
	ds_write_b32 v5, v32 offset:4224
	ds_write_b32 v5, v33 offset:4228
	ds_write_b32 v5, v34 offset:4232
	ds_write_b32 v5, v35 offset:4236
	ds_write_b32 v5, v36 offset:5280
	ds_write_b32 v5, v37 offset:5284
	ds_write_b32 v5, v38 offset:5288
	ds_write_b32 v5, v39 offset:5292
	ds_write_b32 v5, v40 offset:6336
	ds_write_b32 v5, v41 offset:6340
	ds_write_b32 v5, v42 offset:6344
	ds_write_b32 v5, v43 offset:6348
	ds_write_b32 v5, v44 offset:7392
	ds_write_b32 v5, v45 offset:7396
	ds_write_b32 v5, v46 offset:7400
	ds_write_b32 v5, v47 offset:7404
	s_waitcnt lgkmcnt(0)
	ds_read_b32 v16, v6 offset:0
	ds_read_b32 v17, v6 offset:132
	ds_read_b32 v18, v6 offset:264
	ds_read_b32 v19, v6 offset:396
	ds_read_b32 v20, v6 offset:528
	ds_read_b32 v21, v6 offset:660
	ds_read_b32 v22, v6 offset:792
	ds_read_b32 v23, v6 offset:924
	ds_read_b32 v24, v6 offset:32
	ds_read_b32 v25, v6 offset:164
	ds_read_b32 v26, v6 offset:296
	ds_read_b32 v27, v6 offset:428
	ds_read_b32 v28, v6 offset:560
	ds_read_b32 v29, v6 offset:692
	ds_read_b32 v30, v6 offset:824
	ds_read_b32 v31, v6 offset:956
	ds_read_b32 v32, v6 offset:64
	ds_read_b32 v33, v6 offset:196
	ds_read_b32 v34, v6 offset:328
	ds_read_b32 v35, v6 offset:460
	ds_read_b32 v36, v6 offset:592
	ds_read_b32 v37, v6 offset:724
	ds_read_b32 v38, v6 offset:856
	ds_read_b32 v39, v6 offset:988
	ds_read_b32 v40, v6 offset:96
	ds_read_b32 v41, v6 offset:228
	ds_read_b32 v42, v6 offset:360
	ds_read_b32 v43, v6 offset:492
	ds_read_b32 v44, v6 offset:624
	ds_read_b32 v45, v6 offset:756
	ds_read_b32 v46, v6 offset:888
	ds_read_b32 v47, v6 offset:1020
	v_add_u32_e32 v7, s52, v1
	v_lshl_add_u32 v9, v0, 3, s49
	s_cmp_eq_u32 s11, 0
	s_cselect_b32 s54, 0, 1
	s_cmp_eq_u32 s11, 2
	s_cselect_b32 s55, 4, 0
	v_add_u32_e32 v10, 0, v7
	v_lshrrev_b32_e32 v8, 2, v10
	v_and_b32_e32 v14, 3, v10
	v_lshl_add_u32 v8, v8, 3, v14
	v_add_u32_e32 v8, s55, v8
	v_cmp_eq_u32_e64 vcc, s54, 1
	s_nop 1
	v_cndmask_b32_e32 v10, v10, v8, vcc
	v_mul_lo_u32 v10, v10, s15
	v_add_lshl_u32 v10, v10, v9, 1
	v_add_u32_e32 v11, 8, v7
	v_lshrrev_b32_e32 v8, 2, v11
	v_and_b32_e32 v14, 3, v11
	v_lshl_add_u32 v8, v8, 3, v14
	v_add_u32_e32 v8, s55, v8
	v_cmp_eq_u32_e64 vcc, s54, 1
	s_nop 1
	v_cndmask_b32_e32 v11, v11, v8, vcc
	v_mul_lo_u32 v11, v11, s15
	v_add_lshl_u32 v11, v11, v9, 1
	v_add_u32_e32 v12, 16, v7
	v_lshrrev_b32_e32 v8, 2, v12
	v_and_b32_e32 v14, 3, v12
	v_lshl_add_u32 v8, v8, 3, v14
	v_add_u32_e32 v8, s55, v8
	v_cmp_eq_u32_e64 vcc, s54, 1
	s_nop 1
	v_cndmask_b32_e32 v12, v12, v8, vcc
	v_mul_lo_u32 v12, v12, s15
	v_add_lshl_u32 v12, v12, v9, 1
	v_add_u32_e32 v13, 24, v7
	v_lshrrev_b32_e32 v8, 2, v13
	v_and_b32_e32 v14, 3, v13
	v_lshl_add_u32 v8, v8, 3, v14
	v_add_u32_e32 v8, s55, v8
	v_cmp_eq_u32_e64 vcc, s54, 1
	s_nop 1
	v_cndmask_b32_e32 v13, v13, v8, vcc
	v_mul_lo_u32 v13, v13, s15
	v_add_lshl_u32 v13, v13, v9, 1
	s_waitcnt lgkmcnt(0)
	v_cvt_pk_bf16_f32 v52, v16, v17
	v_cvt_pk_bf16_f32 v53, v18, v19
	v_cvt_pk_bf16_f32 v54, v20, v21
	v_cvt_pk_bf16_f32 v55, v22, v23
	v_cvt_pk_bf16_f32 v56, v24, v25
	v_cvt_pk_bf16_f32 v57, v26, v27
	v_cvt_pk_bf16_f32 v58, v28, v29
	v_cvt_pk_bf16_f32 v59, v30, v31
	v_cvt_pk_bf16_f32 v60, v32, v33
	v_cvt_pk_bf16_f32 v61, v34, v35
	v_cvt_pk_bf16_f32 v62, v36, v37
	v_cvt_pk_bf16_f32 v63, v38, v39
	v_cvt_pk_bf16_f32 v64, v40, v41
	v_cvt_pk_bf16_f32 v65, v42, v43
	v_cvt_pk_bf16_f32 v66, v44, v45
	v_cvt_pk_bf16_f32 v67, v46, v47
	global_store_dwordx4 v10, v[52:55], s[42:43] sc1
	global_store_dwordx4 v11, v[56:59], s[42:43] sc1
	global_store_dwordx4 v12, v[60:63], s[42:43] sc1
	global_store_dwordx4 v13, v[64:67], s[42:43] sc1
	s_branch .LBB0_404
